# plus LDS-staged tail K loops for the K=1024 tails of phases 4, 6, 15
# speedup vs baseline: 1.0069x; 1.0038x over previous
; DI f32x16 mfma32(bf16x8 a, bf16x8 b, f32x16 c) { return __builtin_amdgcn_mfma_f32_32x32x16_bf16(a, b, c, 0, 0, 0); }
; DI f32x16 zero16() { f32x16 z; for (int i = 0; i < 16; ++i) z[i] = 0.f; return z; }
; DI int opaque_tid() { int t = threadIdx.x; asm volatile("" : "+v"(t)); return t; }
; template <int EPI, int K, int LNI>
; DI void gemm_tail_unit(const Params& p, const bf16_t* __restrict__ A, const bf16_t* __restrict__ Bt, const int un, float* s_aux) {
;     const int tid = opaque_tid(), lane = tid & 63, w = tid >> 6, r = lane & 31, h = lane >> 5;
;     constexpr int ROW0 = 32768, KS = K / 8;
;     const int col0 = un * 64;
;     if (EPI == EPI_E5B) {
;         if (tid < 64) {
;             const int hd = col0 >> 9;
;             const float* pp = (const float*)((unsigned char*)p.out + OFFO_PART) + (size_t)(ROW0 + tid) * 256 + hd * 64;
;             float sacc = 0.f;
; #pragma unroll
;             for (int i = 0; i < 16; ++i) { const f32x4 v = *(const f32x4*)(pp + i * 4); sacc += (v[0] + v[1]) + (v[2] + v[3]); }
;             s_aux[tid] = __frsqrt_rn(sacc * (1.0f / 512.0f) + 1e-6f);
;         }
;     }
;     f32x16 acc[2][2];
;     acc[0][0] = zero16(); acc[0][1] = zero16(); acc[1][0] = zero16(); acc[1][1] = zero16();
;     const bf16_t* ap = A + (size_t)(ROW0 + r) * K + w * KS + h * 8;
;     const bf16_t* bp = Bt + (size_t)(col0 + r) * K + w * KS + h * 8;
; #pragma unroll 8
;     for (int s = 0; s < KS / 16; ++s) {
;         const bf16x8 a0 = *(const bf16x8*)(ap + s * 16), a1 = *(const bf16x8*)(ap + (size_t)32 * K + s * 16);
;         const bf16x8 b0 = *(const bf16x8*)(bp + s * 16), b1 = *(const bf16x8*)(bp + (size_t)32 * K + s * 16);
;         acc[0][0] = mfma32(a0, b0, acc[0][0]); acc[0][1] = mfma32(a0, b1, acc[0][1]);
;         acc[1][0] = mfma32(a1, b0, acc[1][0]); acc[1][1] = mfma32(a1, b1, acc[1][1]);
;     }
.LBB0_802:
	v_mov_b32_e32 v110, v210
	s_add_i32 s15, s15, s58
	v_ashrrev_i32_e32 v111, 6, v110
	v_and_b32_e32 v112, 31, v110
	v_lshlrev_b32_e32 v0, 7, v111
	v_lshlrev_b32_e32 v80, 11, v112
	v_ashrrev_i32_e32 v1, 31, v0
	v_bfe_u32 v113, v110, 5, 1
	v_lshl_add_u64 v[4:5], s[40:41], 0, v[80:81]
	v_lshlrev_b64 v[0:1], 1, v[0:1]
	v_add_u32_e32 v2, s3, v112
	v_lshlrev_b32_e32 v80, 4, v113
	v_lshl_add_u64 v[4:5], v[4:5], 0, v[0:1]
	v_ashrrev_i32_e32 v3, 31, v2
	v_lshl_add_u64 v[4:5], v[4:5], 0, v[80:81]
	v_lshlrev_b64 v[2:3], 11, v[2:3]
	v_add_co_u32_e32 v8, vcc, s5, v4
	v_lshl_add_u64 v[2:3], s[8:9], 0, v[2:3]
	s_nop 0
	v_addc_co_u32_e32 v9, vcc, 0, v5, vcc
	v_lshl_add_u64 v[0:1], v[2:3], 0, v[0:1]
	v_add_co_u32_e32 v82, vcc, s10, v4
	v_lshl_add_u64 v[86:87], v[0:1], 0, v[80:81]
	s_nop 0
	v_addc_co_u32_e32 v83, vcc, 0, v5, vcc
	v_add_co_u32_e32 v84, vcc, s11, v86
	v_lshl_add_u64 v[88:89], v[4:5], 0, s[0:1]
	s_nop 0
	v_readfirstlane_b32 s88, v8
	v_readfirstlane_b32 s89, v9
	s_nop 0
	v_readfirstlane_b32 s90, v86
	v_readfirstlane_b32 s91, v87
	v_addc_co_u32_e32 v85, vcc, 0, v87, vcc
	v_ashrrev_i32_e32 v114, 7, v110
	v_and_b32_e32 v80, 63, v110
	v_ashrrev_i32_e32 v110, 3, v110
	v_lshlrev_b32_e32 v115, 1, v111
	v_lshl_add_u32 v80, v80, 2, 0
	v_lshlrev_b32_e32 v116, 12, v114
	v_lshl_add_u32 v111, v111, 14, v80
	v_and_b32_e32 v88, 2, v115
	v_or_b32_e32 v89, 1, v88
	v_lshlrev_b32_e32 v86, 2, v113
	v_lshlrev_b32_e32 v87, 5, v114
	v_and_or_b32 v86, v110, s12, v86
	v_and_or_b32 v87, v87, 32, v112
	v_add_u32_e32 v110, 0x10000, v80
	v_add_u32_e32 v112, 0x1c000, v80
	v_add_u32_e32 v100, 0x14000, v80
	v_add_u32_e32 v101, 0x18000, v80
	v_add_u32_e32 v86, 0x8000, v86
	v_add_u32_e32 v98, s3, v87
	v_lshl_or_b32 v87, v88, 10, v116
	v_add_u32_e32 v113, v80, v87
	v_add_u32_e32 v114, v110, v87
	v_add_u32_e32 v115, v100, v87
	v_add_u32_e32 v117, v101, v87
	v_add_u32_e32 v118, v112, v87
	v_or_b32_e32 v95, 0x100, v87
	v_or_b32_e32 v97, 0x200, v87
	v_or_b32_e32 v102, 0x300, v87
	v_lshl_or_b32 v94, v88, 3, v86
	v_lshl_or_b32 v103, v89, 10, v116
	v_lshl_or_b32 v96, v89, 3, v86
	v_ashrrev_i32_e32 v99, 31, v98
	v_add_u32_e32 v104, v110, v97
	v_add_u32_e32 v105, v110, v103
	v_add_u32_e32 v80, v80, v103
	s_add_i32 s3, s3, s4
	s_cmp_lt_i32 s15, 16
	v_or_b32_e32 v109, 0x100, v103
	v_add_u32_e32 v106, v100, v103
	v_add_u32_e32 v107, v101, v103
	v_add_u32_e32 v108, v112, v103
	v_lshl_add_u64 v[76:77], v[98:99], 2, s[16:17]
	v_add_u32_e32 v78, v110, v95
	v_add_u32_e32 v79, v100, v95
	v_add_u32_e32 v98, v101, v95
	v_add_u32_e32 v99, v112, v95
	v_ashrrev_i32_e32 v95, 31, v94
	v_add_u32_e32 v74, v100, v97
	v_add_u32_e32 v75, v101, v97
	v_add_u32_e32 v86, v112, v97
	v_add_u32_e32 v87, v110, v102
	v_add_u32_e32 v88, v100, v102
	v_add_u32_e32 v89, v101, v102
	v_add_u32_e32 v102, v112, v102
	v_ashrrev_i32_e32 v97, 31, v96
	v_lshlrev_b64 v[68:69], 12, v[94:95]
	v_lshl_add_u64 v[68:69], v[76:77], 0, v[68:69]
	v_add_co_u32_e32 v72, vcc, s13, v68
	v_lshlrev_b64 v[70:71], 12, v[96:97]
	s_nop 0
	v_addc_co_u32_e32 v73, vcc, 0, v69, vcc
	v_add_co_u32_e32 v64, vcc, s14, v68
	v_lshl_add_u64 v[70:71], v[76:77], 0, v[70:71]
	s_nop 0
	v_addc_co_u32_e32 v65, vcc, 0, v69, vcc
	v_add_co_u32_e32 v66, vcc, s13, v70
	v_and_b32_e32 v244, 63, v210
	v_lshrrev_b32_e32 v245, 3, v244
	v_and_b32_e32 v249, 7, v244
	v_lshlrev_b32_e32 v247, 11, v245
	v_lshl_add_u32 v247, v249, 4, v247
	v_lshrrev_b32_e32 v248, 6, v210
	v_lshlrev_b32_e32 v248, 14, v248
	v_mul_u32_u24_e32 v245, 0x90, v245
	v_lshl_add_u32 v245, v249, 4, v245
	v_add_u32_e32 v245, v245, v248
	v_and_b32_e32 v246, 31, v210
	v_mul_u32_u24_e32 v246, 0x90, v246
	v_bfe_u32 v249, v210, 5, 1
	v_lshl_add_u32 v246, v249, 4, v246
	v_add_u32_e32 v246, v246, v248
	global_load_dwordx4 v[120:123], v247, s[88:89]
	s_add_u32 s92, s88, 0x4000
	s_addc_u32 s93, s89, 0
	s_nop 0
	global_load_dwordx4 v[124:127], v247, s[92:93]
	s_add_u32 s94, s88, 0x8000
	s_addc_u32 s95, s89, 0
	s_nop 0
	global_load_dwordx4 v[128:131], v247, s[94:95]
	s_add_u32 s92, s88, 0xc000
	s_addc_u32 s93, s89, 0
	s_nop 0
	global_load_dwordx4 v[132:135], v247, s[92:93]
	s_add_u32 s94, s88, 0x10000
	s_addc_u32 s95, s89, 0
	s_nop 0
	global_load_dwordx4 v[136:139], v247, s[94:95]
	s_add_u32 s92, s88, 0x14000
	s_addc_u32 s93, s89, 0
	s_nop 0
	global_load_dwordx4 v[140:143], v247, s[92:93]
	s_add_u32 s94, s88, 0x18000
	s_addc_u32 s95, s89, 0
	s_nop 0
	global_load_dwordx4 v[144:147], v247, s[94:95]
	s_add_u32 s92, s88, 0x1c000
	s_addc_u32 s93, s89, 0
	s_nop 0
	global_load_dwordx4 v[148:151], v247, s[92:93]
	global_load_dwordx4 v[152:155], v247, s[90:91]
	s_add_u32 s94, s90, 0x4000
	s_addc_u32 s95, s91, 0
	s_nop 0
	global_load_dwordx4 v[156:159], v247, s[94:95]
	s_add_u32 s92, s90, 0x8000
	s_addc_u32 s93, s91, 0
	s_nop 0
	global_load_dwordx4 v[160:163], v247, s[92:93]
	s_add_u32 s94, s90, 0xc000
	s_addc_u32 s95, s91, 0
	s_nop 0
	global_load_dwordx4 v[164:167], v247, s[94:95]
	s_add_u32 s92, s90, 0x10000
	s_addc_u32 s93, s91, 0
	s_nop 0
	global_load_dwordx4 v[168:171], v247, s[92:93]
	s_add_u32 s94, s90, 0x14000
	s_addc_u32 s95, s91, 0
	s_nop 0
	global_load_dwordx4 v[172:175], v247, s[94:95]
	s_add_u32 s92, s90, 0x18000
	s_addc_u32 s93, s91, 0
	s_nop 0
	global_load_dwordx4 v[176:179], v247, s[92:93]
	s_add_u32 s94, s90, 0x1c000
	s_addc_u32 s95, s91, 0
	s_nop 0
	global_load_dwordx4 v[180:183], v247, s[94:95]
	global_load_dwordx4 v[184:187], v247, s[88:89] offset:128
	s_add_u32 s92, s88, 0x4000
	s_addc_u32 s93, s89, 0
	s_nop 0
	global_load_dwordx4 v[188:191], v247, s[92:93] offset:128
	s_add_u32 s94, s88, 0x8000
	s_addc_u32 s95, s89, 0
	s_nop 0
	global_load_dwordx4 v[192:195], v247, s[94:95] offset:128
	s_add_u32 s92, s88, 0xc000
	s_addc_u32 s93, s89, 0
	s_nop 0
	global_load_dwordx4 v[196:199], v247, s[92:93] offset:128
	s_add_u32 s94, s88, 0x10000
	s_addc_u32 s95, s89, 0
	s_nop 0
	global_load_dwordx4 v[200:203], v247, s[94:95] offset:128
	s_add_u32 s92, s88, 0x14000
	s_addc_u32 s93, s89, 0
	s_nop 0
	global_load_dwordx4 v[204:207], v247, s[92:93] offset:128
	s_add_u32 s94, s88, 0x18000
	s_addc_u32 s95, s89, 0
	s_nop 0
	global_load_dwordx4 v[212:215], v247, s[94:95] offset:128
	s_add_u32 s92, s88, 0x1c000
	s_addc_u32 s93, s89, 0
	s_nop 0
	global_load_dwordx4 v[216:219], v247, s[92:93] offset:128
	s_waitcnt vmcnt(16) lgkmcnt(0)
; DI f32x16 mfma32(bf16x8 a, bf16x8 b, f32x16 c) { return __builtin_amdgcn_mfma_f32_32x32x16_bf16(a, b, c, 0, 0, 0); }
; template <int EPI, int K, int LNI>
; DI void gemm_tail_unit(const Params& p, const bf16_t* __restrict__ A, const bf16_t* __restrict__ Bt, const int un, float* s_aux) {
;     ...
;     for (int s = 0; s < KS / 16; ++s) {
;         const bf16x8 a0 = *(const bf16x8*)(ap + s * 16), a1 = *(const bf16x8*)(ap + (size_t)32 * K + s * 16);
;         const bf16x8 b0 = *(const bf16x8*)(bp + s * 16), b1 = *(const bf16x8*)(bp + (size_t)32 * K + s * 16);
;         acc[0][0] = mfma32(a0, b0, acc[0][0]); acc[0][1] = mfma32(a0, b1, acc[0][1]);
;         acc[1][0] = mfma32(a1, b0, acc[1][0]); acc[1][1] = mfma32(a1, b1, acc[1][1]);
;     }
	ds_write_b128 v245, v[120:123]
	ds_write_b128 v245, v[124:127] offset:1152
	ds_write_b128 v245, v[128:131] offset:2304
	ds_write_b128 v245, v[132:135] offset:3456
	ds_write_b128 v245, v[136:139] offset:4608
	ds_write_b128 v245, v[140:143] offset:5760
	ds_write_b128 v245, v[144:147] offset:6912
	ds_write_b128 v245, v[148:151] offset:8064
	s_waitcnt lgkmcnt(0)
	ds_read_b128 v[120:123], v246
	ds_read_b128 v[124:127], v246 offset:32
	ds_read_b128 v[128:131], v246 offset:64
	ds_read_b128 v[132:135], v246 offset:96
	ds_read_b128 v[136:139], v246 offset:4608
	ds_read_b128 v[140:143], v246 offset:4640
	ds_read_b128 v[144:147], v246 offset:4672
	ds_read_b128 v[148:151], v246 offset:4704
	s_waitcnt vmcnt(8) lgkmcnt(0)
	ds_write_b128 v245, v[152:155]
	ds_write_b128 v245, v[156:159] offset:1152
	ds_write_b128 v245, v[160:163] offset:2304
	ds_write_b128 v245, v[164:167] offset:3456
	ds_write_b128 v245, v[168:171] offset:4608
	ds_write_b128 v245, v[172:175] offset:5760
	ds_write_b128 v245, v[176:179] offset:6912
	ds_write_b128 v245, v[180:183] offset:8064
	s_waitcnt lgkmcnt(0)
	ds_read_b128 v[152:155], v246
	ds_read_b128 v[156:159], v246 offset:32
	ds_read_b128 v[160:163], v246 offset:64
	ds_read_b128 v[164:167], v246 offset:96
	ds_read_b128 v[168:171], v246 offset:4608
	ds_read_b128 v[172:175], v246 offset:4640
	ds_read_b128 v[176:179], v246 offset:4672
	ds_read_b128 v[180:183], v246 offset:4704
	s_waitcnt lgkmcnt(0)
	v_mfma_f32_32x32x16_bf16 v[48:63], v[120:123], v[152:155], 0
	v_mfma_f32_32x32x16_bf16 v[32:47], v[120:123], v[168:171], 0
	v_mfma_f32_32x32x16_bf16 v[16:31], v[136:139], v[152:155], 0
	v_mfma_f32_32x32x16_bf16 v[0:15], v[136:139], v[168:171], 0
	v_mfma_f32_32x32x16_bf16 v[48:63], v[124:127], v[156:159], v[48:63]
	v_mfma_f32_32x32x16_bf16 v[32:47], v[124:127], v[172:175], v[32:47]
	v_mfma_f32_32x32x16_bf16 v[16:31], v[140:143], v[156:159], v[16:31]
	v_mfma_f32_32x32x16_bf16 v[0:15], v[140:143], v[172:175], v[0:15]
	v_mfma_f32_32x32x16_bf16 v[48:63], v[128:131], v[160:163], v[48:63]
	v_mfma_f32_32x32x16_bf16 v[32:47], v[128:131], v[176:179], v[32:47]
	v_mfma_f32_32x32x16_bf16 v[16:31], v[144:147], v[160:163], v[16:31]
	v_mfma_f32_32x32x16_bf16 v[0:15], v[144:147], v[176:179], v[0:15]
	v_mfma_f32_32x32x16_bf16 v[48:63], v[132:135], v[164:167], v[48:63]
	v_mfma_f32_32x32x16_bf16 v[32:47], v[132:135], v[180:183], v[32:47]
	v_mfma_f32_32x32x16_bf16 v[16:31], v[148:151], v[164:167], v[16:31]
	v_mfma_f32_32x32x16_bf16 v[0:15], v[148:151], v[180:183], v[0:15]
	global_load_dwordx4 v[120:123], v247, s[90:91] offset:128
	s_add_u32 s94, s90, 0x4000
	s_addc_u32 s95, s91, 0
	s_nop 0
	global_load_dwordx4 v[124:127], v247, s[94:95] offset:128
	s_add_u32 s92, s90, 0x8000
	s_addc_u32 s93, s91, 0
	s_nop 0
	global_load_dwordx4 v[128:131], v247, s[92:93] offset:128
	s_add_u32 s94, s90, 0xc000
	s_addc_u32 s95, s91, 0
	s_nop 0
	global_load_dwordx4 v[132:135], v247, s[94:95] offset:128
	s_add_u32 s92, s90, 0x10000
	s_addc_u32 s93, s91, 0
	s_nop 0
	global_load_dwordx4 v[136:139], v247, s[92:93] offset:128
	s_add_u32 s94, s90, 0x14000
	s_addc_u32 s95, s91, 0
	s_nop 0
	global_load_dwordx4 v[140:143], v247, s[94:95] offset:128
	s_add_u32 s92, s90, 0x18000
	s_addc_u32 s93, s91, 0
	s_nop 0
	global_load_dwordx4 v[144:147], v247, s[92:93] offset:128
	s_add_u32 s94, s90, 0x1c000
	s_addc_u32 s95, s91, 0
	s_nop 0
	global_load_dwordx4 v[148:151], v247, s[94:95] offset:128
	s_waitcnt vmcnt(8) lgkmcnt(0)
	ds_write_b128 v245, v[184:187]
	ds_write_b128 v245, v[188:191] offset:1152
	ds_write_b128 v245, v[192:195] offset:2304
	ds_write_b128 v245, v[196:199] offset:3456
	ds_write_b128 v245, v[200:203] offset:4608
	ds_write_b128 v245, v[204:207] offset:5760
	ds_write_b128 v245, v[212:215] offset:6912
	ds_write_b128 v245, v[216:219] offset:8064
	s_waitcnt lgkmcnt(0)
	ds_read_b128 v[184:187], v246
	ds_read_b128 v[188:191], v246 offset:32
	ds_read_b128 v[192:195], v246 offset:64
	ds_read_b128 v[196:199], v246 offset:96
	ds_read_b128 v[200:203], v246 offset:4608
	ds_read_b128 v[204:207], v246 offset:4640
	ds_read_b128 v[212:215], v246 offset:4672
	ds_read_b128 v[216:219], v246 offset:4704
	s_waitcnt vmcnt(0) lgkmcnt(0)
	ds_write_b128 v245, v[120:123]
	ds_write_b128 v245, v[124:127] offset:1152
	ds_write_b128 v245, v[128:131] offset:2304
	ds_write_b128 v245, v[132:135] offset:3456
	ds_write_b128 v245, v[136:139] offset:4608
	ds_write_b128 v245, v[140:143] offset:5760
	ds_write_b128 v245, v[144:147] offset:6912
	ds_write_b128 v245, v[148:151] offset:8064
	s_waitcnt lgkmcnt(0)
	ds_read_b128 v[120:123], v246
	ds_read_b128 v[124:127], v246 offset:32
	ds_read_b128 v[128:131], v246 offset:64
	ds_read_b128 v[132:135], v246 offset:96
	ds_read_b128 v[136:139], v246 offset:4608
	ds_read_b128 v[140:143], v246 offset:4640
	ds_read_b128 v[144:147], v246 offset:4672
	ds_read_b128 v[148:151], v246 offset:4704
	s_waitcnt lgkmcnt(0)
; DI f32x16 mfma32(bf16x8 a, bf16x8 b, f32x16 c) { return __builtin_amdgcn_mfma_f32_32x32x16_bf16(a, b, c, 0, 0, 0); }
; template <int EPI, int K, int LNI>
; DI void gemm_tail_unit(const Params& p, const bf16_t* __restrict__ A, const bf16_t* __restrict__ Bt, const int un, float* s_aux) {
;     ...
;     for (int s = 0; s < KS / 16; ++s) {
;         const bf16x8 a0 = *(const bf16x8*)(ap + s * 16), a1 = *(const bf16x8*)(ap + (size_t)32 * K + s * 16);
;         const bf16x8 b0 = *(const bf16x8*)(bp + s * 16), b1 = *(const bf16x8*)(bp + (size_t)32 * K + s * 16);
;         acc[0][0] = mfma32(a0, b0, acc[0][0]); acc[0][1] = mfma32(a0, b1, acc[0][1]);
;         acc[1][0] = mfma32(a1, b0, acc[1][0]); acc[1][1] = mfma32(a1, b1, acc[1][1]);
;     }
;     float* red = (float*)dsm;
; #pragma unroll
;     for (int i = 0; i < 2; ++i)
; #pragma unroll
;         for (int j = 0; j < 2; ++j)
; #pragma unroll
;             for (int reg = 0; reg < 16; ++reg) red[((w * 4 + i * 2 + j) * 16 + reg) * 64 + lane] = acc[i][j][reg];
;     __syncthreads();
	v_mfma_f32_32x32x16_bf16 v[48:63], v[184:187], v[120:123], v[48:63]
	v_mfma_f32_32x32x16_bf16 v[32:47], v[184:187], v[136:139], v[32:47]
	v_mfma_f32_32x32x16_bf16 v[16:31], v[200:203], v[120:123], v[16:31]
	v_mfma_f32_32x32x16_bf16 v[0:15], v[200:203], v[136:139], v[0:15]
	v_mfma_f32_32x32x16_bf16 v[48:63], v[188:191], v[124:127], v[48:63]
	v_mfma_f32_32x32x16_bf16 v[32:47], v[188:191], v[140:143], v[32:47]
	v_mfma_f32_32x32x16_bf16 v[16:31], v[204:207], v[124:127], v[16:31]
	v_mfma_f32_32x32x16_bf16 v[0:15], v[204:207], v[140:143], v[0:15]
	v_mfma_f32_32x32x16_bf16 v[48:63], v[192:195], v[128:131], v[48:63]
	v_mfma_f32_32x32x16_bf16 v[32:47], v[192:195], v[144:147], v[32:47]
	v_mfma_f32_32x32x16_bf16 v[16:31], v[212:215], v[128:131], v[16:31]
	v_mfma_f32_32x32x16_bf16 v[0:15], v[212:215], v[144:147], v[0:15]
	v_mfma_f32_32x32x16_bf16 v[48:63], v[196:199], v[132:135], v[48:63]
	v_mfma_f32_32x32x16_bf16 v[32:47], v[196:199], v[148:151], v[32:47]
	v_mfma_f32_32x32x16_bf16 v[16:31], v[216:219], v[132:135], v[16:31]
	v_mfma_f32_32x32x16_bf16 v[0:15], v[216:219], v[148:151], v[0:15]
	s_nop 7
	s_nop 3
	s_cmp_lt_i32 s15, 16
	ds_write2st64_b32 v111, v48, v49 offset1:1
	ds_write2st64_b32 v111, v50, v51 offset0:2 offset1:3
	ds_write2st64_b32 v111, v52, v53 offset0:4 offset1:5
	ds_write2st64_b32 v111, v54, v55 offset0:6 offset1:7
	ds_write2st64_b32 v111, v56, v57 offset0:8 offset1:9
	ds_write2st64_b32 v111, v58, v59 offset0:10 offset1:11
	ds_write2st64_b32 v111, v60, v61 offset0:12 offset1:13
	ds_write2st64_b32 v111, v62, v63 offset0:14 offset1:15
	ds_write2st64_b32 v111, v32, v33 offset0:16 offset1:17
	ds_write2st64_b32 v111, v34, v35 offset0:18 offset1:19
	ds_write2st64_b32 v111, v36, v37 offset0:20 offset1:21
	ds_write2st64_b32 v111, v38, v39 offset0:22 offset1:23
	ds_write2st64_b32 v111, v40, v41 offset0:24 offset1:25
	ds_write2st64_b32 v111, v42, v43 offset0:26 offset1:27
	ds_write2st64_b32 v111, v44, v45 offset0:28 offset1:29
	ds_write2st64_b32 v111, v46, v47 offset0:30 offset1:31
	ds_write2st64_b32 v111, v16, v17 offset0:32 offset1:33
	ds_write2st64_b32 v111, v18, v19 offset0:34 offset1:35
	ds_write2st64_b32 v111, v20, v21 offset0:36 offset1:37
	ds_write2st64_b32 v111, v22, v23 offset0:38 offset1:39
	ds_write2st64_b32 v111, v24, v25 offset0:40 offset1:41
	ds_write2st64_b32 v111, v26, v27 offset0:42 offset1:43
	ds_write2st64_b32 v111, v28, v29 offset0:44 offset1:45
	ds_write2st64_b32 v111, v30, v31 offset0:46 offset1:47
	ds_write2st64_b32 v111, v0, v1 offset0:48 offset1:49
	ds_write2st64_b32 v111, v2, v3 offset0:50 offset1:51
	ds_write2st64_b32 v111, v4, v5 offset0:52 offset1:53
	ds_write2st64_b32 v111, v6, v7 offset0:54 offset1:55
	ds_write2st64_b32 v111, v8, v9 offset0:56 offset1:57
	ds_write2st64_b32 v111, v10, v11 offset0:58 offset1:59
	ds_write2st64_b32 v111, v12, v13 offset0:60 offset1:61
	ds_write2st64_b32 v111, v14, v15 offset0:62 offset1:63
	s_waitcnt lgkmcnt(0)
	s_barrier
; DI float ex2(float x) { return __builtin_amdgcn_exp2f(x); }
;     ...
;     } else if (EPI == EPI_RESID) {
;         float* d = (float*)(p.ws + OFF_H) + (size_t)row0 * 1024 + col;
; #pragma unroll
;         for (int e = 0; e < 4; ++e) {
;             float hprev = d[(size_t)e * 1024];
;             if (LNI >= 0) hprev = (hprev - rs[e][0]) * rs[e][1] * gg + bb;
;             d[(size_t)e * 1024] = ALPHA * hprev + v[e];
;         }
; template <int EPI, int K, int LNI>
; DI void gemm_tail_unit(const Params& p, const bf16_t* __restrict__ A, const bf16_t* __restrict__ Bt, const int un, float* s_aux) {
;     ...
;     {
;         const int tile = w >> 1, i = tile >> 1, j = tile & 1;
; #pragma unroll
;         for (int gg = 0; gg < 2; ++gg) {
;             const int g = 2 * (w & 1) + gg;
;             float v[4];
; #pragma unroll
;             for (int e = 0; e < 4; ++e) {
;                 float sacc = 0.f;
; #pragma unroll
;                 for (int wv = 0; wv < 8; ++wv) sacc += red[((wv * 4 + tile) * 16 + 4 * g + e) * 64 + lane];
;                 v[e] = sacc;
;             }
;             const int lrow0 = i * 32 + 8 * g + 4 * h;
;             f32x2 rs[4]; float lng = 1.f, lnb = 0.f;
;             if (EPI == EPI_E5) {
;                 lng = log2f(1.f - ex2(-5.f - (float)((col0 >> 8) & 3)));
;                 const int idx_ = (((ROW0 + lrow0) % LT) + 48) & 63;
; #pragma unroll
;                 for (int e = 0; e < 4; ++e) rs[e] = (f32x2){ex2(lng * (float)(idx_ + e + 1)), 0.0625f * ex2(lng * (float)(63 - idx_ - e))};
;             }
;             if (EPI == EPI_RESID && LNI >= 0) {
;                 const f32x2* st_ = (const f32x2*)((unsigned char*)p.out + OFFO_STATS) + ROW0 + lrow0;
; #pragma unroll
;                 for (int e = 0; e < 4; ++e) rs[e] = st_[e];
;                 lng = p.ln_g[(LNI < 0 ? 0 : LNI) * 1024 + col0 + j * 32 + r]; lnb = p.ln_b[(LNI < 0 ? 0 : LNI) * 1024 + col0 + j * 32 + r];
;             }
;             epi_store<EPI, LNI>(p, ROW0 + lrow0, col0 + j * 32 + r, lrow0, v, s_aux, rs, lng, lnb);
	global_load_dword v18, v[68:69], off
	global_load_dword v19, v[72:73], off offset:-4096
	global_load_dword v20, v[72:73], off
	global_load_dword v21, v[64:65], off
	ds_read_b32 v22, v114
	ds_read_b32 v23, v115
	ds_read_b32 v24, v117
	ds_read_b32 v25, v118
	ds_read_b32 v26, v78
	ds_read_b32 v27, v79
	ds_read_b32 v28, v98
	ds_read_b32 v29, v99
	ds_read2st64_b32 v[2:3], v113 offset1:1
	ds_read2st64_b32 v[4:5], v113 offset0:64 offset1:65
	ds_read2st64_b32 v[6:7], v113 offset0:66 offset1:67
	ds_read2st64_b32 v[8:9], v113 offset0:2 offset1:3
	ds_read2st64_b32 v[10:11], v113 offset0:128 offset1:129
	ds_read2st64_b32 v[12:13], v113 offset0:192 offset1:193
	ds_read2st64_b32 v[14:15], v113 offset0:194 offset1:195
	ds_read2st64_b32 v[16:17], v113 offset0:130 offset1:131
	ds_read_b32 v30, v104
	ds_read_b32 v31, v74
	ds_read_b32 v32, v75
	ds_read_b32 v33, v86
	ds_read_b32 v34, v87
	ds_read_b32 v35, v88
	ds_read_b32 v36, v89
	ds_read_b32 v37, v102
	s_waitcnt lgkmcnt(14)
	v_add_f32_e32 v2, 0, v2
	v_add_f32_e32 v3, 0, v3
	s_waitcnt lgkmcnt(12)
	v_add_f32_e32 v8, 0, v8
	v_add_f32_e32 v9, 0, v9
	v_add_f32_e32 v2, v2, v4
	v_add_f32_e32 v3, v3, v5
	v_add_f32_e32 v4, v8, v6
	v_add_f32_e32 v5, v9, v7
	s_waitcnt lgkmcnt(11)
	v_add_f32_e32 v2, v2, v10
	v_add_f32_e32 v3, v3, v11
	s_waitcnt lgkmcnt(8)
	v_add_f32_e32 v4, v4, v16
	v_add_f32_e32 v5, v5, v17
	v_add_f32_e32 v2, v2, v12
	v_add_f32_e32 v3, v3, v13
	v_add_f32_e32 v4, v4, v14
	v_add_f32_e32 v5, v5, v15
	v_add_f32_e32 v2, v2, v22
	v_add_f32_e32 v3, v3, v26
	s_waitcnt lgkmcnt(7)
	v_add_f32_e32 v4, v4, v30
	s_waitcnt lgkmcnt(3)
	v_add_f32_e32 v5, v5, v34
	v_add_f32_e32 v2, v2, v23
	v_add_f32_e32 v3, v3, v27
	v_add_f32_e32 v4, v4, v31
	s_waitcnt lgkmcnt(2)
	v_add_f32_e32 v5, v5, v35
	v_add_f32_e32 v2, v2, v24
	v_add_f32_e32 v3, v3, v28
	v_add_f32_e32 v4, v4, v32
	s_waitcnt lgkmcnt(1)
	v_add_f32_e32 v5, v5, v36
	v_add_f32_e32 v2, v2, v25
	v_addc_co_u32_e32 v67, vcc, 0, v71, vcc
	v_add_f32_e32 v3, v3, v29
	v_add_f32_e32 v4, v4, v33
	s_waitcnt lgkmcnt(0)
	v_add_f32_e32 v5, v5, v37
	v_add_co_u32_e32 v0, vcc, 0x3000, v70
	v_add_u32_e32 v6, v101, v109
	s_nop 0
	v_addc_co_u32_e32 v1, vcc, 0, v71, vcc
	v_add_u32_e32 v7, v112, v109
	s_waitcnt vmcnt(3)
	v_fmac_f32_e32 v2, 0x3fb504f3, v18
	s_waitcnt vmcnt(2)
	v_fmac_f32_e32 v3, 0x3fb504f3, v19
	s_waitcnt vmcnt(1)
	v_fmac_f32_e32 v4, 0x3fb504f3, v20
	s_waitcnt vmcnt(0)
	v_fmac_f32_e32 v5, 0x3fb504f3, v21
	global_store_dword v[68:69], v2, off
	global_store_dword v[72:73], v3, off offset:-4096
	global_store_dword v[72:73], v4, off
	global_store_dword v[64:65], v5, off
	global_load_dword v18, v[70:71], off
	global_load_dword v19, v[66:67], off offset:-4096
	global_load_dword v20, v[66:67], off
	global_load_dword v21, v[0:1], off
	v_or_b32_e32 v2, 0x200, v103
	v_or_b32_e32 v3, 0x300, v103
	v_add_u32_e32 v4, v110, v109
	v_add_u32_e32 v5, v100, v109
	v_add_u32_e32 v22, v110, v2
	v_add_u32_e32 v23, v100, v2
	v_add_u32_e32 v24, v101, v2
	v_add_u32_e32 v25, v112, v2
	v_add_u32_e32 v26, v110, v3
	v_add_u32_e32 v27, v100, v3
	v_add_u32_e32 v28, v101, v3
	v_add_u32_e32 v29, v112, v3
	ds_read_b32 v30, v105
	ds_read_b32 v31, v106
	ds_read_b32 v32, v107
	ds_read_b32 v33, v108
	ds_read_b32 v34, v4
	ds_read_b32 v35, v5
	ds_read_b32 v36, v6
	ds_read_b32 v37, v7
	ds_read2st64_b32 v[2:3], v80 offset1:1
	ds_read2st64_b32 v[4:5], v80 offset0:64 offset1:65
	ds_read2st64_b32 v[6:7], v80 offset0:66 offset1:67
	ds_read2st64_b32 v[8:9], v80 offset0:2 offset1:3
	ds_read2st64_b32 v[10:11], v80 offset0:128 offset1:129
	ds_read2st64_b32 v[12:13], v80 offset0:192 offset1:193
	ds_read2st64_b32 v[14:15], v80 offset0:194 offset1:195
	ds_read2st64_b32 v[16:17], v80 offset0:130 offset1:131
	ds_read_b32 v22, v22
	ds_read_b32 v23, v23
	ds_read_b32 v24, v24
	ds_read_b32 v25, v25
	ds_read_b32 v26, v26
	ds_read_b32 v27, v27
	ds_read_b32 v28, v28
	ds_read_b32 v29, v29
	s_waitcnt lgkmcnt(14)
	v_add_f32_e32 v2, 0, v2
	v_add_f32_e32 v3, 0, v3
	s_waitcnt lgkmcnt(12)
	v_add_f32_e32 v8, 0, v8
	v_add_f32_e32 v9, 0, v9
	v_add_f32_e32 v2, v2, v4
	v_add_f32_e32 v3, v3, v5
	v_add_f32_e32 v4, v8, v6
	v_add_f32_e32 v5, v9, v7
	s_waitcnt lgkmcnt(11)
	v_add_f32_e32 v2, v2, v10
	v_add_f32_e32 v3, v3, v11
	s_waitcnt lgkmcnt(8)
	v_add_f32_e32 v4, v4, v16
	v_add_f32_e32 v5, v5, v17
	v_add_f32_e32 v2, v2, v12
	v_add_f32_e32 v3, v3, v13
	v_add_f32_e32 v4, v4, v14
	v_add_f32_e32 v5, v5, v15
	v_add_f32_e32 v2, v2, v30
	v_add_f32_e32 v3, v3, v34
	s_waitcnt lgkmcnt(7)
	v_add_f32_e32 v4, v4, v22
	s_waitcnt lgkmcnt(3)
	v_add_f32_e32 v5, v5, v26
	v_add_f32_e32 v2, v2, v31
	v_add_f32_e32 v3, v3, v35
	v_add_f32_e32 v4, v4, v23
	s_waitcnt lgkmcnt(2)
	v_add_f32_e32 v5, v5, v27
	v_add_f32_e32 v2, v2, v32
	v_add_f32_e32 v3, v3, v36
	v_add_f32_e32 v4, v4, v24
	s_waitcnt lgkmcnt(1)
	v_add_f32_e32 v5, v5, v28
	v_add_f32_e32 v2, v2, v33
	v_add_f32_e32 v3, v3, v37
	v_add_f32_e32 v4, v4, v25
	s_waitcnt lgkmcnt(0)
	v_add_f32_e32 v5, v5, v29
	s_waitcnt vmcnt(3)
	v_fmac_f32_e32 v2, 0x3fb504f3, v18
	s_waitcnt vmcnt(2)
	v_fmac_f32_e32 v3, 0x3fb504f3, v19
	s_waitcnt vmcnt(1)
	v_fmac_f32_e32 v4, 0x3fb504f3, v20
	s_waitcnt vmcnt(0)
	v_fmac_f32_e32 v5, 0x3fb504f3, v21
	global_store_dword v[70:71], v2, off
	global_store_dword v[66:67], v3, off offset:-4096
	global_store_dword v[66:67], v4, off
	global_store_dword v[0:1], v5, off
	s_barrier
	s_cbranch_scc1 .LBB0_802

; DI f32x16 mfma32(bf16x8 a, bf16x8 b, f32x16 c) { return __builtin_amdgcn_mfma_f32_32x32x16_bf16(a, b, c, 0, 0, 0); }
; DI f32x16 zero16() { f32x16 z; for (int i = 0; i < 16; ++i) z[i] = 0.f; return z; }
; DI int opaque_tid() { int t = threadIdx.x; asm volatile("" : "+v"(t)); return t; }
; template <int EPI, int K, int LNI>
; DI void gemm_tail_unit(const Params& p, const bf16_t* __restrict__ A, const bf16_t* __restrict__ Bt, const int un, float* s_aux) {
;     const int tid = opaque_tid(), lane = tid & 63, w = tid >> 6, r = lane & 31, h = lane >> 5;
;     constexpr int ROW0 = 32768, KS = K / 8;
;     const int col0 = un * 64;
;     if (EPI == EPI_E5B) {
;         if (tid < 64) {
;             const int hd = col0 >> 9;
;             const float* pp = (const float*)((unsigned char*)p.out + OFFO_PART) + (size_t)(ROW0 + tid) * 256 + hd * 64;
;             float sacc = 0.f;
; #pragma unroll
;             for (int i = 0; i < 16; ++i) { const f32x4 v = *(const f32x4*)(pp + i * 4); sacc += (v[0] + v[1]) + (v[2] + v[3]); }
;             s_aux[tid] = __frsqrt_rn(sacc * (1.0f / 512.0f) + 1e-6f);
;         }
;     }
;     f32x16 acc[2][2];
;     acc[0][0] = zero16(); acc[0][1] = zero16(); acc[1][0] = zero16(); acc[1][1] = zero16();
;     const bf16_t* ap = A + (size_t)(ROW0 + r) * K + w * KS + h * 8;
;     const bf16_t* bp = Bt + (size_t)(col0 + r) * K + w * KS + h * 8;
; #pragma unroll 8
;     for (int s = 0; s < KS / 16; ++s) {
;         const bf16x8 a0 = *(const bf16x8*)(ap + s * 16), a1 = *(const bf16x8*)(ap + (size_t)32 * K + s * 16);
;         const bf16x8 b0 = *(const bf16x8*)(bp + s * 16), b1 = *(const bf16x8*)(bp + (size_t)32 * K + s * 16);
;         acc[0][0] = mfma32(a0, b0, acc[0][0]); acc[0][1] = mfma32(a0, b1, acc[0][1]);
;         acc[1][0] = mfma32(a1, b0, acc[1][0]); acc[1][1] = mfma32(a1, b1, acc[1][1]);
;     }
.LBB0_936:
	v_mov_b32_e32 v106, v210
	s_add_i32 s18, s18, s58
	v_ashrrev_i32_e32 v110, 6, v106
	v_and_b32_e32 v111, 31, v106
	v_lshlrev_b32_e32 v0, 7, v110
	v_add_u32_e32 v2, s3, v111
	v_lshlrev_b32_e32 v88, 11, v111
	v_ashrrev_i32_e32 v1, 31, v0
	v_ashrrev_i32_e32 v3, 31, v2
	v_bfe_u32 v107, v106, 5, 1
	v_lshl_add_u64 v[4:5], s[40:41], 0, v[88:89]
	v_lshlrev_b64 v[0:1], 1, v[0:1]
	v_lshlrev_b64 v[2:3], 11, v[2:3]
	v_lshlrev_b32_e32 v88, 4, v107
	v_lshl_add_u64 v[4:5], v[4:5], 0, v[0:1]
	v_lshl_add_u64 v[2:3], s[8:9], 0, v[2:3]
	v_lshl_add_u64 v[4:5], v[4:5], 0, v[88:89]
	v_lshl_add_u64 v[0:1], v[2:3], 0, v[0:1]
	v_lshl_add_u64 v[94:95], v[0:1], 0, v[88:89]
	v_add_co_u32_e32 v0, vcc, s5, v4
	v_lshl_add_u64 v[96:97], v[4:5], 0, s[0:1]
	s_nop 0
	v_addc_co_u32_e32 v1, vcc, 0, v5, vcc
	v_add_co_u32_e32 v90, vcc, s10, v4
	v_and_b32_e32 v88, 63, v106
	s_nop 0
	v_addc_co_u32_e32 v91, vcc, 0, v5, vcc
	v_add_co_u32_e32 v92, vcc, s11, v94
	s_nop 0
	v_readfirstlane_b32 s88, v0
	v_readfirstlane_b32 s89, v1
	s_nop 0
	s_nop 0
	v_readfirstlane_b32 s90, v94
	v_readfirstlane_b32 s91, v95
	v_addc_co_u32_e32 v93, vcc, 0, v95, vcc
	v_ashrrev_i32_e32 v112, 3, v106
	v_lshlrev_b32_e32 v115, 2, v107
	v_lshlrev_b32_e32 v113, 1, v110
	v_lshl_add_u32 v88, v88, 2, 0
	v_lshl_add_u32 v117, v110, 14, v88
	v_add_u32_e32 v118, 0x14000, v88
	v_add_u32_e32 v119, 0x18000, v88
	v_add_u32_e32 v120, 0x1c000, v88
	v_ashrrev_i32_e32 v80, 7, v106
	v_lshlrev_b32_e32 v114, 12, v80
	v_lshlrev_b32_e32 v116, 5, v80
	v_and_or_b32 v80, v112, s12, v115
	v_and_or_b32 v81, v116, 32, v111
	v_and_b32_e32 v82, 2, v113
	v_add_u32_e32 v83, 0x8000, v80
	v_add_u32_e32 v80, s3, v81
	v_ashrrev_i32_e32 v81, 31, v80
	v_add_u32_e32 v116, 0x10000, v88
	v_lshl_or_b32 v110, v82, 3, v83
	s_add_i32 s3, s3, s4
	s_cmp_lt_i32 s18, 64
	v_or_b32_e32 v99, 1, v82
	v_lshl_or_b32 v98, v82, 10, v114
	v_lshl_or_b32 v127, v99, 10, v114
	v_lshl_or_b32 v112, v99, 3, v83
	v_lshl_add_u64 v[114:115], v[80:81], 1, s[36:37]
	v_add_u32_e32 v121, v88, v98
	v_add_u32_e32 v122, v116, v98
	v_add_u32_e32 v123, v118, v98
	v_add_u32_e32 v124, v119, v98
	v_add_u32_e32 v125, v120, v98
	v_or_b32_e32 v111, 0x100, v98
	v_or_b32_e32 v113, 0x200, v98
	v_or_b32_e32 v126, 0x300, v98
	v_add_u32_e32 v128, v116, v111
	v_add_u32_e32 v129, v120, v111
	v_add_u32_e32 v88, v88, v127
	v_add_u32_e32 v134, v118, v127
	v_add_u32_e32 v135, v119, v127
	v_add_u32_e32 v136, v120, v127
	v_or_b32_e32 v137, 0x200, v127
	v_add_u32_e32 v130, v116, v113
	v_add_u32_e32 v131, v118, v113
	v_add_u32_e32 v132, v119, v113
	v_add_u32_e32 v133, v120, v113
	v_ashrrev_i32_e32 v113, 31, v112
	v_add_u32_e32 v96, v118, v111
	v_add_u32_e32 v97, v119, v111
	v_ashrrev_i32_e32 v111, 31, v110
	v_or_b32_e32 v76, 0x100, v127
	v_add_u32_e32 v102, v116, v76
	v_add_u32_e32 v103, v118, v76
	v_add_u32_e32 v104, v119, v76
	v_add_u32_e32 v105, v120, v76
	v_lshlrev_b64 v[94:95], 13, v[110:111]
	v_add_u32_e32 v110, v116, v137
	v_add_u32_e32 v98, v116, v126
	v_add_u32_e32 v99, v118, v126
	v_add_u32_e32 v100, v119, v126
	v_add_u32_e32 v101, v120, v126
	v_add_u32_e32 v126, v116, v127
	v_or_b32_e32 v127, 0x300, v127
	v_add_u32_e32 v111, v118, v127
	v_add_u32_e32 v106, v118, v137
	v_add_u32_e32 v107, v119, v137
	v_add_u32_e32 v108, v120, v137
	v_add_u32_e32 v109, v116, v127
	v_add_u32_e32 v116, v119, v127
	v_add_u32_e32 v118, v120, v127
	v_lshl_add_u64 v[74:75], v[114:115], 0, v[94:95]
	v_lshlrev_b64 v[72:73], 13, v[112:113]
	v_lshl_add_u64 v[72:73], v[114:115], 0, v[72:73]
	v_add_co_u32_e32 v76, vcc, s13, v74
	s_nop 1
	v_addc_co_u32_e32 v77, vcc, 0, v75, vcc
	v_add_co_u32_e32 v78, vcc, s14, v74
	s_nop 0
	v_addc_co_u32_e32 v79, vcc, 0, v75, vcc
	v_add_co_u32_e32 v80, vcc, s15, v74
	s_nop 1
	v_addc_co_u32_e32 v81, vcc, 0, v75, vcc
	v_add_co_u32_e32 v68, vcc, s13, v72
	s_nop 1
	v_addc_co_u32_e32 v69, vcc, 0, v73, vcc
	v_add_co_u32_e32 v70, vcc, s14, v72
	v_addc_co_u32_e32 v71, vcc, 0, v73, vcc
	v_add_co_u32_e32 v64, vcc, 0x6000, v72
	s_nop 1
	v_addc_co_u32_e32 v65, vcc, 0, v73, vcc
	v_and_b32_e32 v244, 63, v210
	v_lshrrev_b32_e32 v245, 3, v244
	v_and_b32_e32 v249, 7, v244
	v_lshlrev_b32_e32 v247, 11, v245
	v_lshl_add_u32 v247, v249, 4, v247
	v_lshrrev_b32_e32 v248, 6, v210
	v_lshlrev_b32_e32 v248, 14, v248
	v_mul_u32_u24_e32 v245, 0x90, v245
	v_lshl_add_u32 v245, v249, 4, v245
	v_add_u32_e32 v245, v245, v248
	v_and_b32_e32 v246, 31, v210
	v_mul_u32_u24_e32 v246, 0x90, v246
	v_bfe_u32 v249, v210, 5, 1
	v_lshl_add_u32 v246, v249, 4, v246
	v_add_u32_e32 v246, v246, v248
	global_load_dwordx4 v[84:87], v247, s[88:89]
	s_add_u32 s92, s88, 0x4000
	s_addc_u32 s93, s89, 0
	s_nop 0
	global_load_dwordx4 v[140:143], v247, s[92:93]
	s_add_u32 s94, s88, 0x8000
	s_addc_u32 s95, s89, 0
	s_nop 0
	global_load_dwordx4 v[144:147], v247, s[94:95]
	s_add_u32 s92, s88, 0xc000
	s_addc_u32 s93, s89, 0
	s_nop 0
	global_load_dwordx4 v[148:151], v247, s[92:93]
	s_add_u32 s94, s88, 0x10000
	s_addc_u32 s95, s89, 0
	s_nop 0
	global_load_dwordx4 v[152:155], v247, s[94:95]
	s_add_u32 s92, s88, 0x14000
	s_addc_u32 s93, s89, 0
	s_nop 0
	global_load_dwordx4 v[156:159], v247, s[92:93]
	s_add_u32 s94, s88, 0x18000
	s_addc_u32 s95, s89, 0
	s_nop 0
	global_load_dwordx4 v[160:163], v247, s[94:95]
	s_add_u32 s92, s88, 0x1c000
	s_addc_u32 s93, s89, 0
	s_nop 0
	global_load_dwordx4 v[164:167], v247, s[92:93]
	global_load_dwordx4 v[168:171], v247, s[90:91]
	s_add_u32 s94, s90, 0x4000
	s_addc_u32 s95, s91, 0
	s_nop 0
	global_load_dwordx4 v[172:175], v247, s[94:95]
	s_add_u32 s92, s90, 0x8000
	s_addc_u32 s93, s91, 0
	s_nop 0
	global_load_dwordx4 v[176:179], v247, s[92:93]
	s_add_u32 s94, s90, 0xc000
	s_addc_u32 s95, s91, 0
	s_nop 0
; DI f32x16 mfma32(bf16x8 a, bf16x8 b, f32x16 c) { return __builtin_amdgcn_mfma_f32_32x32x16_bf16(a, b, c, 0, 0, 0); }
; template <int EPI, int K, int LNI>
; DI void gemm_tail_unit(const Params& p, const bf16_t* __restrict__ A, const bf16_t* __restrict__ Bt, const int un, float* s_aux) {
;     ...
; #pragma unroll 8
;     for (int s = 0; s < KS / 16; ++s) {
;         const bf16x8 a0 = *(const bf16x8*)(ap + s * 16), a1 = *(const bf16x8*)(ap + (size_t)32 * K + s * 16);
;         const bf16x8 b0 = *(const bf16x8*)(bp + s * 16), b1 = *(const bf16x8*)(bp + (size_t)32 * K + s * 16);
;         acc[0][0] = mfma32(a0, b0, acc[0][0]); acc[0][1] = mfma32(a0, b1, acc[0][1]);
;         acc[1][0] = mfma32(a1, b0, acc[1][0]); acc[1][1] = mfma32(a1, b1, acc[1][1]);
;     }
	global_load_dwordx4 v[180:183], v247, s[94:95]
	s_add_u32 s92, s90, 0x10000
	s_addc_u32 s93, s91, 0
	s_nop 0
	global_load_dwordx4 v[184:187], v247, s[92:93]
	s_add_u32 s94, s90, 0x14000
	s_addc_u32 s95, s91, 0
	s_nop 0
	global_load_dwordx4 v[188:191], v247, s[94:95]
	s_add_u32 s92, s90, 0x18000
	s_addc_u32 s93, s91, 0
	s_nop 0
	global_load_dwordx4 v[192:195], v247, s[92:93]
	s_add_u32 s94, s90, 0x1c000
	s_addc_u32 s95, s91, 0
	s_nop 0
	global_load_dwordx4 v[196:199], v247, s[94:95]
	global_load_dwordx4 v[200:203], v247, s[88:89] offset:128
	s_add_u32 s92, s88, 0x4000
	s_addc_u32 s93, s89, 0
	s_nop 0
	global_load_dwordx4 v[204:207], v247, s[92:93] offset:128
	s_add_u32 s94, s88, 0x8000
	s_addc_u32 s95, s89, 0
	s_nop 0
	global_load_dwordx4 v[212:215], v247, s[94:95] offset:128
	s_add_u32 s92, s88, 0xc000
	s_addc_u32 s93, s89, 0
	s_nop 0
	global_load_dwordx4 v[216:219], v247, s[92:93] offset:128
	s_add_u32 s94, s88, 0x10000
	s_addc_u32 s95, s89, 0
	s_nop 0
	global_load_dwordx4 v[220:223], v247, s[94:95] offset:128
	s_add_u32 s92, s88, 0x14000
	s_addc_u32 s93, s89, 0
	s_nop 0
	global_load_dwordx4 v[224:227], v247, s[92:93] offset:128
	s_add_u32 s94, s88, 0x18000
	s_addc_u32 s95, s89, 0
	s_nop 0
	global_load_dwordx4 v[228:231], v247, s[94:95] offset:128
	s_add_u32 s92, s88, 0x1c000
	s_addc_u32 s93, s89, 0
	s_nop 0
	global_load_dwordx4 v[232:235], v247, s[92:93] offset:128
	s_waitcnt vmcnt(16) lgkmcnt(0)
	ds_write_b128 v245, v[84:87]
	ds_write_b128 v245, v[140:143] offset:1152
	ds_write_b128 v245, v[144:147] offset:2304
	ds_write_b128 v245, v[148:151] offset:3456
	ds_write_b128 v245, v[152:155] offset:4608
	ds_write_b128 v245, v[156:159] offset:5760
	ds_write_b128 v245, v[160:163] offset:6912
	ds_write_b128 v245, v[164:167] offset:8064
	s_waitcnt lgkmcnt(0)
	ds_read_b128 v[84:87], v246
	ds_read_b128 v[140:143], v246 offset:32
	ds_read_b128 v[144:147], v246 offset:64
	ds_read_b128 v[148:151], v246 offset:96
	ds_read_b128 v[152:155], v246 offset:4608
	ds_read_b128 v[156:159], v246 offset:4640
	ds_read_b128 v[160:163], v246 offset:4672
	ds_read_b128 v[164:167], v246 offset:4704
	s_waitcnt vmcnt(8) lgkmcnt(0)
	ds_write_b128 v245, v[168:171]
	ds_write_b128 v245, v[172:175] offset:1152
	ds_write_b128 v245, v[176:179] offset:2304
	ds_write_b128 v245, v[180:183] offset:3456
	ds_write_b128 v245, v[184:187] offset:4608
	ds_write_b128 v245, v[188:191] offset:5760
	ds_write_b128 v245, v[192:195] offset:6912
	ds_write_b128 v245, v[196:199] offset:8064
	s_waitcnt lgkmcnt(0)
	ds_read_b128 v[168:171], v246
	ds_read_b128 v[172:175], v246 offset:32
	ds_read_b128 v[176:179], v246 offset:64
	ds_read_b128 v[180:183], v246 offset:96
	ds_read_b128 v[184:187], v246 offset:4608
	ds_read_b128 v[188:191], v246 offset:4640
	ds_read_b128 v[192:195], v246 offset:4672
	ds_read_b128 v[196:199], v246 offset:4704
	s_waitcnt lgkmcnt(0)
	v_mfma_f32_32x32x16_bf16 v[48:63], v[84:87], v[168:171], 0
	v_mfma_f32_32x32x16_bf16 v[32:47], v[84:87], v[184:187], 0
	v_mfma_f32_32x32x16_bf16 v[16:31], v[152:155], v[168:171], 0
	v_mfma_f32_32x32x16_bf16 v[0:15], v[152:155], v[184:187], 0
	v_mfma_f32_32x32x16_bf16 v[48:63], v[140:143], v[172:175], v[48:63]
	v_mfma_f32_32x32x16_bf16 v[32:47], v[140:143], v[188:191], v[32:47]
	v_mfma_f32_32x32x16_bf16 v[16:31], v[156:159], v[172:175], v[16:31]
	v_mfma_f32_32x32x16_bf16 v[0:15], v[156:159], v[188:191], v[0:15]
	v_mfma_f32_32x32x16_bf16 v[48:63], v[144:147], v[176:179], v[48:63]
	v_mfma_f32_32x32x16_bf16 v[32:47], v[144:147], v[192:195], v[32:47]
	v_mfma_f32_32x32x16_bf16 v[16:31], v[160:163], v[176:179], v[16:31]
	v_mfma_f32_32x32x16_bf16 v[0:15], v[160:163], v[192:195], v[0:15]
	v_mfma_f32_32x32x16_bf16 v[48:63], v[148:151], v[180:183], v[48:63]
	v_mfma_f32_32x32x16_bf16 v[32:47], v[148:151], v[196:199], v[32:47]
	v_mfma_f32_32x32x16_bf16 v[16:31], v[164:167], v[180:183], v[16:31]
	v_mfma_f32_32x32x16_bf16 v[0:15], v[164:167], v[196:199], v[0:15]
	global_load_dwordx4 v[84:87], v247, s[90:91] offset:128
	s_add_u32 s94, s90, 0x4000
	s_addc_u32 s95, s91, 0
	s_nop 0
	global_load_dwordx4 v[140:143], v247, s[94:95] offset:128
	s_add_u32 s92, s90, 0x8000
	s_addc_u32 s93, s91, 0
	s_nop 0
	global_load_dwordx4 v[144:147], v247, s[92:93] offset:128
	s_add_u32 s94, s90, 0xc000
	s_addc_u32 s95, s91, 0
	s_nop 0
	global_load_dwordx4 v[148:151], v247, s[94:95] offset:128
	s_add_u32 s92, s90, 0x10000
	s_addc_u32 s93, s91, 0
	s_nop 0
	global_load_dwordx4 v[152:155], v247, s[92:93] offset:128
	s_add_u32 s94, s90, 0x14000
	s_addc_u32 s95, s91, 0
	s_nop 0
	global_load_dwordx4 v[156:159], v247, s[94:95] offset:128
	s_add_u32 s92, s90, 0x18000
	s_addc_u32 s93, s91, 0
	s_nop 0
	global_load_dwordx4 v[160:163], v247, s[92:93] offset:128
	s_add_u32 s94, s90, 0x1c000
	s_addc_u32 s95, s91, 0
	s_nop 0
	global_load_dwordx4 v[164:167], v247, s[94:95] offset:128
	s_waitcnt vmcnt(8) lgkmcnt(0)
	ds_write_b128 v245, v[200:203]
	ds_write_b128 v245, v[204:207] offset:1152
	ds_write_b128 v245, v[212:215] offset:2304
	ds_write_b128 v245, v[216:219] offset:3456
	ds_write_b128 v245, v[220:223] offset:4608
	ds_write_b128 v245, v[224:227] offset:5760
	ds_write_b128 v245, v[228:231] offset:6912
	ds_write_b128 v245, v[232:235] offset:8064
	s_waitcnt lgkmcnt(0)
	ds_read_b128 v[200:203], v246
	ds_read_b128 v[204:207], v246 offset:32
	ds_read_b128 v[212:215], v246 offset:64
	ds_read_b128 v[216:219], v246 offset:96
	ds_read_b128 v[220:223], v246 offset:4608
	ds_read_b128 v[224:227], v246 offset:4640
	ds_read_b128 v[228:231], v246 offset:4672
	ds_read_b128 v[232:235], v246 offset:4704
	s_waitcnt vmcnt(0) lgkmcnt(0)
; DI f32x16 mfma32(bf16x8 a, bf16x8 b, f32x16 c) { return __builtin_amdgcn_mfma_f32_32x32x16_bf16(a, b, c, 0, 0, 0); }
; template <int EPI, int K, int LNI>
; DI void gemm_tail_unit(const Params& p, const bf16_t* __restrict__ A, const bf16_t* __restrict__ Bt, const int un, float* s_aux) {
;     ...
; #pragma unroll 8
;     for (int s = 0; s < KS / 16; ++s) {
;         const bf16x8 a0 = *(const bf16x8*)(ap + s * 16), a1 = *(const bf16x8*)(ap + (size_t)32 * K + s * 16);
;         const bf16x8 b0 = *(const bf16x8*)(bp + s * 16), b1 = *(const bf16x8*)(bp + (size_t)32 * K + s * 16);
;         acc[0][0] = mfma32(a0, b0, acc[0][0]); acc[0][1] = mfma32(a0, b1, acc[0][1]);
;         acc[1][0] = mfma32(a1, b0, acc[1][0]); acc[1][1] = mfma32(a1, b1, acc[1][1]);
;     }
;     float* red = (float*)dsm;
; #pragma unroll
;     for (int i = 0; i < 2; ++i)
; #pragma unroll
;         for (int j = 0; j < 2; ++j)
; #pragma unroll
;             for (int reg = 0; reg < 16; ++reg) red[((w * 4 + i * 2 + j) * 16 + reg) * 64 + lane] = acc[i][j][reg];
	ds_write_b128 v245, v[84:87]
	ds_write_b128 v245, v[140:143] offset:1152
	ds_write_b128 v245, v[144:147] offset:2304
	ds_write_b128 v245, v[148:151] offset:3456
	ds_write_b128 v245, v[152:155] offset:4608
	ds_write_b128 v245, v[156:159] offset:5760
	ds_write_b128 v245, v[160:163] offset:6912
	ds_write_b128 v245, v[164:167] offset:8064
	s_waitcnt lgkmcnt(0)
	ds_read_b128 v[84:87], v246
	ds_read_b128 v[140:143], v246 offset:32
	ds_read_b128 v[144:147], v246 offset:64
	ds_read_b128 v[148:151], v246 offset:96
	ds_read_b128 v[152:155], v246 offset:4608
	ds_read_b128 v[156:159], v246 offset:4640
	ds_read_b128 v[160:163], v246 offset:4672
	ds_read_b128 v[164:167], v246 offset:4704
	s_waitcnt lgkmcnt(0)
	v_mfma_f32_32x32x16_bf16 v[48:63], v[200:203], v[84:87], v[48:63]
	v_mfma_f32_32x32x16_bf16 v[32:47], v[200:203], v[152:155], v[32:47]
	v_mfma_f32_32x32x16_bf16 v[16:31], v[220:223], v[84:87], v[16:31]
	v_mfma_f32_32x32x16_bf16 v[0:15], v[220:223], v[152:155], v[0:15]
	v_mfma_f32_32x32x16_bf16 v[48:63], v[204:207], v[140:143], v[48:63]
	v_mfma_f32_32x32x16_bf16 v[32:47], v[204:207], v[156:159], v[32:47]
	v_mfma_f32_32x32x16_bf16 v[16:31], v[224:227], v[140:143], v[16:31]
	v_mfma_f32_32x32x16_bf16 v[0:15], v[224:227], v[156:159], v[0:15]
	v_mfma_f32_32x32x16_bf16 v[48:63], v[212:215], v[144:147], v[48:63]
	v_mfma_f32_32x32x16_bf16 v[32:47], v[212:215], v[160:163], v[32:47]
	v_mfma_f32_32x32x16_bf16 v[16:31], v[228:231], v[144:147], v[16:31]
	v_mfma_f32_32x32x16_bf16 v[0:15], v[228:231], v[160:163], v[0:15]
	v_mfma_f32_32x32x16_bf16 v[48:63], v[216:219], v[148:151], v[48:63]
	v_mfma_f32_32x32x16_bf16 v[32:47], v[216:219], v[164:167], v[32:47]
	v_mfma_f32_32x32x16_bf16 v[16:31], v[232:235], v[148:151], v[16:31]
	v_mfma_f32_32x32x16_bf16 v[0:15], v[232:235], v[164:167], v[0:15]
	s_nop 7
	s_nop 3
	s_cmp_lt_i32 s18, 64
	ds_write2st64_b32 v117, v48, v49 offset1:1
	ds_write2st64_b32 v117, v50, v51 offset0:2 offset1:3
	ds_write2st64_b32 v117, v52, v53 offset0:4 offset1:5
	ds_write2st64_b32 v117, v54, v55 offset0:6 offset1:7
	ds_write2st64_b32 v117, v56, v57 offset0:8 offset1:9
	ds_write2st64_b32 v117, v58, v59 offset0:10 offset1:11
	ds_write2st64_b32 v117, v60, v61 offset0:12 offset1:13
	ds_write2st64_b32 v117, v62, v63 offset0:14 offset1:15
	ds_write2st64_b32 v117, v32, v33 offset0:16 offset1:17
	ds_write2st64_b32 v117, v34, v35 offset0:18 offset1:19
	ds_write2st64_b32 v117, v36, v37 offset0:20 offset1:21
	ds_write2st64_b32 v117, v38, v39 offset0:22 offset1:23
	ds_write2st64_b32 v117, v40, v41 offset0:24 offset1:25
	ds_write2st64_b32 v117, v42, v43 offset0:26 offset1:27
	ds_write2st64_b32 v117, v44, v45 offset0:28 offset1:29
	ds_write2st64_b32 v117, v46, v47 offset0:30 offset1:31
	ds_write2st64_b32 v117, v16, v17 offset0:32 offset1:33
	ds_write2st64_b32 v117, v18, v19 offset0:34 offset1:35
	ds_write2st64_b32 v117, v20, v21 offset0:36 offset1:37
	ds_write2st64_b32 v117, v22, v23 offset0:38 offset1:39
	ds_write2st64_b32 v117, v24, v25 offset0:40 offset1:41
	ds_write2st64_b32 v117, v26, v27 offset0:42 offset1:43
	ds_write2st64_b32 v117, v28, v29 offset0:44 offset1:45
	ds_write2st64_b32 v117, v30, v31 offset0:46 offset1:47
	ds_write2st64_b32 v117, v0, v1 offset0:48 offset1:49
	ds_write2st64_b32 v117, v2, v3 offset0:50 offset1:51
	ds_write2st64_b32 v117, v4, v5 offset0:52 offset1:53
	ds_write2st64_b32 v117, v6, v7 offset0:54 offset1:55
	ds_write2st64_b32 v117, v8, v9 offset0:56 offset1:57
	ds_write2st64_b32 v117, v10, v11 offset0:58 offset1:59
	ds_write2st64_b32 v117, v12, v13 offset0:60 offset1:61
	ds_write2st64_b32 v117, v14, v15 offset0:62 offset1:63
	s_waitcnt lgkmcnt(0)
	s_barrier
; DI bf16_t f2bf(float x) { return (bf16_t)(cvt_pk(x, 0.f) & 0xffffu); }
;     ...
;     } else if (EPI == EPI_FFN1) {
;         bf16_t* d = (bf16_t*)(p.ws + OFF_U) + (size_t)row0 * 4096 + col;
; #pragma unroll
;         for (int e = 0; e < 4; ++e) { const float t = fmaxf(v[e], 0.f); d[(size_t)e * 4096] = f2bf(t * t); }
; template <int EPI, int K, int LNI>
; DI void gemm_tail_unit(const Params& p, const bf16_t* __restrict__ A, const bf16_t* __restrict__ Bt, const int un, float* s_aux) {
;     ...
;     {
;         const int tile = w >> 1, i = tile >> 1, j = tile & 1;
; #pragma unroll
;         for (int gg = 0; gg < 2; ++gg) {
;             const int g = 2 * (w & 1) + gg;
;             float v[4];
; #pragma unroll
;             for (int e = 0; e < 4; ++e) {
;                 float sacc = 0.f;
; #pragma unroll
;                 for (int wv = 0; wv < 8; ++wv) sacc += red[((wv * 4 + tile) * 16 + 4 * g + e) * 64 + lane];
;                 v[e] = sacc;
;             }
;             const int lrow0 = i * 32 + 8 * g + 4 * h;
	ds_read_b32 v32, v122
	ds_read_b32 v33, v123
	ds_read_b32 v34, v124
	ds_read_b32 v35, v125
	ds_read_b32 v36, v128
	ds_read_b32 v37, v96
	ds_read_b32 v38, v97
	ds_read_b32 v39, v129
	ds_read2st64_b32 v[0:1], v121 offset1:1
	ds_read2st64_b32 v[2:3], v121 offset0:64 offset1:65
	ds_read2st64_b32 v[4:5], v121 offset0:66 offset1:67
	ds_read2st64_b32 v[6:7], v121 offset0:2 offset1:3
	ds_read2st64_b32 v[8:9], v121 offset0:128 offset1:129
	ds_read2st64_b32 v[10:11], v121 offset0:192 offset1:193
	ds_read2st64_b32 v[12:13], v121 offset0:194 offset1:195
	ds_read2st64_b32 v[14:15], v121 offset0:130 offset1:131
	ds_read_b32 v40, v130
	ds_read_b32 v41, v131
	ds_read_b32 v42, v132
	ds_read_b32 v43, v133
	ds_read_b32 v44, v98
	ds_read_b32 v45, v99
	ds_read_b32 v46, v100
	ds_read_b32 v47, v101
	ds_read_b32 v48, v126
	ds_read_b32 v49, v134
	ds_read_b32 v50, v135
	ds_read_b32 v51, v136
	ds_read_b32 v52, v102
	ds_read_b32 v53, v103
	ds_read_b32 v54, v104
	ds_read_b32 v55, v105
	ds_read2st64_b32 v[16:17], v88 offset1:1
	ds_read2st64_b32 v[18:19], v88 offset0:64 offset1:65
	ds_read2st64_b32 v[20:21], v88 offset0:66 offset1:67
	ds_read2st64_b32 v[22:23], v88 offset0:2 offset1:3
	ds_read2st64_b32 v[24:25], v88 offset0:128 offset1:129
	ds_read2st64_b32 v[26:27], v88 offset0:192 offset1:193
	ds_read2st64_b32 v[28:29], v88 offset0:194 offset1:195
	ds_read2st64_b32 v[30:31], v88 offset0:130 offset1:131
	ds_read_b32 v56, v110
	ds_read_b32 v57, v106
	ds_read_b32 v58, v107
	ds_read_b32 v59, v108
	ds_read_b32 v60, v109
	ds_read_b32 v61, v111
	ds_read_b32 v62, v116
	ds_read_b32 v63, v118
	s_waitcnt lgkmcnt(14)
	v_add_f32_e32 v0, 0, v0
	v_add_f32_e32 v1, 0, v1
	v_add_f32_e32 v6, 0, v6
	v_add_f32_e32 v7, 0, v7
	v_add_f32_e32 v16, 0, v16
	v_add_f32_e32 v17, 0, v17
	s_waitcnt lgkmcnt(12)
	v_add_f32_e32 v22, 0, v22
	v_add_f32_e32 v23, 0, v23
	v_add_f32_e32 v0, v0, v2
	v_add_f32_e32 v1, v1, v3
	v_add_f32_e32 v2, v6, v4
	v_add_f32_e32 v3, v7, v5
	v_add_f32_e32 v4, v16, v18
	v_add_f32_e32 v5, v17, v19
	v_add_f32_e32 v6, v22, v20
	v_add_f32_e32 v7, v23, v21
	v_add_f32_e32 v0, v0, v8
	v_add_f32_e32 v1, v1, v9
	v_add_f32_e32 v2, v2, v14
	v_add_f32_e32 v3, v3, v15
	s_waitcnt lgkmcnt(11)
	v_add_f32_e32 v4, v4, v24
	v_add_f32_e32 v5, v5, v25
	s_waitcnt lgkmcnt(8)
	v_add_f32_e32 v6, v6, v30
	v_add_f32_e32 v7, v7, v31
	v_add_f32_e32 v0, v0, v10
	v_add_f32_e32 v1, v1, v11
	v_add_f32_e32 v2, v2, v12
	v_add_f32_e32 v3, v3, v13
	v_add_f32_e32 v4, v4, v26
	v_add_f32_e32 v5, v5, v27
	v_add_f32_e32 v6, v6, v28
	v_add_f32_e32 v7, v7, v29
	v_add_f32_e32 v0, v0, v32
	v_add_f32_e32 v1, v1, v36
	v_add_f32_e32 v2, v2, v40
	v_add_f32_e32 v3, v3, v44
	v_add_f32_e32 v4, v4, v48
	v_add_f32_e32 v5, v5, v52
	s_waitcnt lgkmcnt(7)
	v_add_f32_e32 v6, v6, v56
	s_waitcnt lgkmcnt(3)
	v_add_f32_e32 v7, v7, v60
	v_add_f32_e32 v0, v0, v33
	v_add_f32_e32 v1, v1, v37
	v_add_f32_e32 v2, v2, v41
	v_add_f32_e32 v3, v3, v45
	v_add_f32_e32 v4, v4, v49
	v_add_f32_e32 v5, v5, v53
	v_add_f32_e32 v6, v6, v57
	s_waitcnt lgkmcnt(2)
	v_add_f32_e32 v7, v7, v61
	v_add_f32_e32 v0, v0, v34
	v_add_f32_e32 v1, v1, v38
	v_add_f32_e32 v2, v2, v42
	v_add_f32_e32 v3, v3, v46
	v_add_f32_e32 v4, v4, v50
	v_add_f32_e32 v5, v5, v54
	v_add_f32_e32 v6, v6, v58
	s_waitcnt lgkmcnt(1)
	v_add_f32_e32 v7, v7, v62
	v_add_f32_e32 v0, v0, v35
	v_add_f32_e32 v1, v1, v39
	v_add_f32_e32 v2, v2, v43
	v_add_f32_e32 v3, v3, v47
	v_add_f32_e32 v4, v4, v51
	v_add_f32_e32 v5, v5, v55
	v_add_f32_e32 v6, v6, v59
	s_waitcnt lgkmcnt(0)
	v_add_f32_e32 v7, v7, v63
	v_max_f32_e32 v0, 0, v0
	v_max_f32_e32 v1, 0, v1
	v_max_f32_e32 v2, 0, v2
	v_max_f32_e32 v3, 0, v3
	v_max_f32_e32 v4, 0, v4
	v_max_f32_e32 v5, 0, v5
	v_max_f32_e32 v6, 0, v6
	v_max_f32_e32 v7, 0, v7
	v_mul_f32_e32 v0, v0, v0
	v_mul_f32_e32 v1, v1, v1
	v_mul_f32_e32 v2, v2, v2
	v_mul_f32_e32 v3, v3, v3
	v_mul_f32_e32 v4, v4, v4
	v_mul_f32_e32 v5, v5, v5
	v_mul_f32_e32 v6, v6, v6
	v_mul_f32_e32 v7, v7, v7
	v_cvt_pk_bf16_f32 v0, v0, s0
	v_cvt_pk_bf16_f32 v1, v1, s0
	v_cvt_pk_bf16_f32 v2, v2, s0
	v_cvt_pk_bf16_f32 v3, v3, s0
	v_cvt_pk_bf16_f32 v4, v4, s0
	v_cvt_pk_bf16_f32 v5, v5, s0
	v_cvt_pk_bf16_f32 v6, v6, s0
	v_cvt_pk_bf16_f32 v7, v7, s0
	global_store_short v[74:75], v0, off
	global_store_short v[76:77], v1, off
	global_store_short v[78:79], v2, off
	global_store_short v[80:81], v3, off
	global_store_short v[72:73], v4, off
	global_store_short v[68:69], v5, off
	global_store_short v[70:71], v6, off
	global_store_short v[64:65], v7, off
	s_barrier
	s_cbranch_scc1 .LBB0_936

; DI f32x16 mfma32(bf16x8 a, bf16x8 b, f32x16 c) { return __builtin_amdgcn_mfma_f32_32x32x16_bf16(a, b, c, 0, 0, 0); }
; DI f32x16 zero16() { f32x16 z; for (int i = 0; i < 16; ++i) z[i] = 0.f; return z; }
; DI int opaque_tid() { int t = threadIdx.x; asm volatile("" : "+v"(t)); return t; }
; template <int EPI, int K, int LNI>
; DI void gemm_tail_unit(const Params& p, const bf16_t* __restrict__ A, const bf16_t* __restrict__ Bt, const int un, float* s_aux) {
;     const int tid = opaque_tid(), lane = tid & 63, w = tid >> 6, r = lane & 31, h = lane >> 5;
;     constexpr int ROW0 = 32768, KS = K / 8;
;     const int col0 = un * 64;
;     if (EPI == EPI_E5B) {
;         if (tid < 64) {
;             const int hd = col0 >> 9;
;             const float* pp = (const float*)((unsigned char*)p.out + OFFO_PART) + (size_t)(ROW0 + tid) * 256 + hd * 64;
;             float sacc = 0.f;
; #pragma unroll
;             for (int i = 0; i < 16; ++i) { const f32x4 v = *(const f32x4*)(pp + i * 4); sacc += (v[0] + v[1]) + (v[2] + v[3]); }
;             s_aux[tid] = __frsqrt_rn(sacc * (1.0f / 512.0f) + 1e-6f);
;         }
;     }
;     f32x16 acc[2][2];
;     acc[0][0] = zero16(); acc[0][1] = zero16(); acc[1][0] = zero16(); acc[1][1] = zero16();
;     const bf16_t* ap = A + (size_t)(ROW0 + r) * K + w * KS + h * 8;
;     const bf16_t* bp = Bt + (size_t)(col0 + r) * K + w * KS + h * 8;
; #pragma unroll 8
;     for (int s = 0; s < KS / 16; ++s) {
;         const bf16x8 a0 = *(const bf16x8*)(ap + s * 16), a1 = *(const bf16x8*)(ap + (size_t)32 * K + s * 16);
;         const bf16x8 b0 = *(const bf16x8*)(bp + s * 16), b1 = *(const bf16x8*)(bp + (size_t)32 * K + s * 16);
;         acc[0][0] = mfma32(a0, b0, acc[0][0]); acc[0][1] = mfma32(a0, b1, acc[0][1]);
;         acc[1][0] = mfma32(a1, b0, acc[1][0]); acc[1][1] = mfma32(a1, b1, acc[1][1]);
;     }
.LBB0_1861:
	v_mov_b32_e32 v106, v210
	s_add_i32 s20, s20, s58
	v_ashrrev_i32_e32 v110, 6, v106
	v_and_b32_e32 v111, 31, v106
	v_lshlrev_b32_e32 v0, 7, v110
	v_lshlrev_b32_e32 v88, 11, v111
	v_ashrrev_i32_e32 v1, 31, v0
	v_bfe_u32 v107, v106, 5, 1
	v_lshl_add_u64 v[4:5], s[40:41], 0, v[88:89]
	v_lshlrev_b64 v[0:1], 1, v[0:1]
	v_add_u32_e32 v2, s3, v111
	v_lshlrev_b32_e32 v88, 4, v107
	v_lshl_add_u64 v[4:5], v[4:5], 0, v[0:1]
	v_ashrrev_i32_e32 v3, 31, v2
	v_lshl_add_u64 v[4:5], v[4:5], 0, v[88:89]
	v_lshlrev_b64 v[2:3], 11, v[2:3]
	v_add_co_u32_e32 v8, vcc, s7, v4
	v_lshl_add_u64 v[2:3], s[10:11], 0, v[2:3]
	s_nop 0
	v_addc_co_u32_e32 v9, vcc, 0, v5, vcc
	v_lshl_add_u64 v[0:1], v[2:3], 0, v[0:1]
	v_add_co_u32_e32 v90, vcc, s8, v4
	v_lshl_add_u64 v[94:95], v[0:1], 0, v[88:89]
	s_nop 0
	v_addc_co_u32_e32 v91, vcc, 0, v5, vcc
	v_add_co_u32_e32 v92, vcc, s9, v94
	v_lshl_add_u64 v[96:97], v[4:5], 0, s[4:5]
	s_nop 0
	v_readfirstlane_b32 s88, v8
	v_readfirstlane_b32 s89, v9
	s_nop 0
	v_readfirstlane_b32 s90, v94
	v_readfirstlane_b32 s91, v95
	v_addc_co_u32_e32 v93, vcc, 0, v95, vcc
	v_and_b32_e32 v88, 63, v106
	v_ashrrev_i32_e32 v112, 3, v106
	v_lshlrev_b32_e32 v115, 2, v107
	v_lshlrev_b32_e32 v113, 1, v110
	v_lshl_add_u32 v88, v88, 2, 0
	v_lshl_add_u32 v117, v110, 14, v88
	v_add_u32_e32 v118, 0x14000, v88
	v_add_u32_e32 v119, 0x18000, v88
	v_add_u32_e32 v120, 0x1c000, v88
	v_ashrrev_i32_e32 v80, 7, v106
	v_lshlrev_b32_e32 v114, 12, v80
	v_lshlrev_b32_e32 v116, 5, v80
	v_and_or_b32 v80, v112, s12, v115
	v_and_or_b32 v81, v116, 32, v111
	v_and_b32_e32 v82, 2, v113
	v_add_u32_e32 v83, 0x8000, v80
	v_add_u32_e32 v80, s3, v81
	v_ashrrev_i32_e32 v81, 31, v80
	v_add_u32_e32 v116, 0x10000, v88
	v_lshl_or_b32 v110, v82, 3, v83
	s_add_i32 s3, s3, s6
	s_cmp_lt_i32 s20, 64
	v_or_b32_e32 v99, 1, v82
	v_lshl_or_b32 v98, v82, 10, v114
	v_lshl_or_b32 v127, v99, 10, v114
	v_lshl_or_b32 v112, v99, 3, v83
	v_lshl_add_u64 v[114:115], v[80:81], 1, s[36:37]
	v_add_u32_e32 v121, v88, v98
	v_add_u32_e32 v122, v116, v98
	v_add_u32_e32 v123, v118, v98
	v_add_u32_e32 v124, v119, v98
	v_add_u32_e32 v125, v120, v98
	v_or_b32_e32 v111, 0x100, v98
	v_or_b32_e32 v113, 0x200, v98
	v_or_b32_e32 v126, 0x300, v98
	v_add_u32_e32 v128, v116, v111
	v_add_u32_e32 v129, v120, v111
	v_add_u32_e32 v88, v88, v127
	v_add_u32_e32 v134, v118, v127
	v_add_u32_e32 v135, v119, v127
	v_add_u32_e32 v136, v120, v127
	v_or_b32_e32 v137, 0x200, v127
	v_add_u32_e32 v130, v116, v113
	v_add_u32_e32 v131, v118, v113
	v_add_u32_e32 v132, v119, v113
	v_add_u32_e32 v133, v120, v113
	v_ashrrev_i32_e32 v113, 31, v112
	v_add_u32_e32 v96, v118, v111
	v_add_u32_e32 v97, v119, v111
	v_ashrrev_i32_e32 v111, 31, v110
	v_or_b32_e32 v76, 0x100, v127
	v_add_u32_e32 v102, v116, v76
	v_add_u32_e32 v103, v118, v76
	v_add_u32_e32 v104, v119, v76
	v_add_u32_e32 v105, v120, v76
	v_lshlrev_b64 v[94:95], 13, v[110:111]
	v_add_u32_e32 v110, v116, v137
	v_add_u32_e32 v98, v116, v126
	v_add_u32_e32 v99, v118, v126
	v_add_u32_e32 v100, v119, v126
	v_add_u32_e32 v101, v120, v126
	v_add_u32_e32 v126, v116, v127
	v_or_b32_e32 v127, 0x300, v127
	v_add_u32_e32 v111, v118, v127
	v_add_u32_e32 v106, v118, v137
	v_add_u32_e32 v107, v119, v137
	v_add_u32_e32 v108, v120, v137
	v_add_u32_e32 v109, v116, v127
	v_add_u32_e32 v116, v119, v127
	v_add_u32_e32 v118, v120, v127
	v_lshl_add_u64 v[74:75], v[114:115], 0, v[94:95]
	v_lshlrev_b64 v[72:73], 13, v[112:113]
	v_lshl_add_u64 v[72:73], v[114:115], 0, v[72:73]
	v_add_co_u32_e32 v76, vcc, s13, v74
	s_nop 1
	v_addc_co_u32_e32 v77, vcc, 0, v75, vcc
	v_add_co_u32_e32 v78, vcc, s14, v74
	s_nop 0
	v_addc_co_u32_e32 v79, vcc, 0, v75, vcc
	v_add_co_u32_e32 v80, vcc, s15, v74
	s_nop 1
	v_addc_co_u32_e32 v81, vcc, 0, v75, vcc
	v_add_co_u32_e32 v68, vcc, s13, v72
	s_nop 1
	v_addc_co_u32_e32 v69, vcc, 0, v73, vcc
	v_add_co_u32_e32 v70, vcc, s14, v72
	v_addc_co_u32_e32 v71, vcc, 0, v73, vcc
	v_add_co_u32_e32 v64, vcc, 0x6000, v72
	s_nop 1
	v_addc_co_u32_e32 v65, vcc, 0, v73, vcc
	v_and_b32_e32 v244, 63, v210
	v_lshrrev_b32_e32 v245, 3, v244
	v_and_b32_e32 v249, 7, v244
	v_lshlrev_b32_e32 v247, 11, v245
	v_lshl_add_u32 v247, v249, 4, v247
	v_lshrrev_b32_e32 v248, 6, v210
	v_lshlrev_b32_e32 v248, 14, v248
	v_mul_u32_u24_e32 v245, 0x90, v245
	v_lshl_add_u32 v245, v249, 4, v245
	v_add_u32_e32 v245, v245, v248
	v_and_b32_e32 v246, 31, v210
	v_mul_u32_u24_e32 v246, 0x90, v246
	v_bfe_u32 v249, v210, 5, 1
	v_lshl_add_u32 v246, v249, 4, v246
	v_add_u32_e32 v246, v246, v248
	global_load_dwordx4 v[84:87], v247, s[88:89]
	s_add_u32 s92, s88, 0x4000
	s_addc_u32 s93, s89, 0
	s_nop 0
	global_load_dwordx4 v[140:143], v247, s[92:93]
	s_add_u32 s94, s88, 0x8000
	s_addc_u32 s95, s89, 0
	s_nop 0
	global_load_dwordx4 v[144:147], v247, s[94:95]
	s_add_u32 s92, s88, 0xc000
	s_addc_u32 s93, s89, 0
	s_nop 0
	global_load_dwordx4 v[148:151], v247, s[92:93]
	s_add_u32 s94, s88, 0x10000
	s_addc_u32 s95, s89, 0
	s_nop 0
	global_load_dwordx4 v[152:155], v247, s[94:95]
	s_add_u32 s92, s88, 0x14000
	s_addc_u32 s93, s89, 0
	s_nop 0
	global_load_dwordx4 v[156:159], v247, s[92:93]
	s_add_u32 s94, s88, 0x18000
	s_addc_u32 s95, s89, 0
	s_nop 0
	global_load_dwordx4 v[160:163], v247, s[94:95]
	s_add_u32 s92, s88, 0x1c000
	s_addc_u32 s93, s89, 0
	s_nop 0
	global_load_dwordx4 v[164:167], v247, s[92:93]
	global_load_dwordx4 v[168:171], v247, s[90:91]
	s_add_u32 s94, s90, 0x4000
	s_addc_u32 s95, s91, 0
	s_nop 0
	global_load_dwordx4 v[172:175], v247, s[94:95]
	s_add_u32 s92, s90, 0x8000
	s_addc_u32 s93, s91, 0
	s_nop 0
	global_load_dwordx4 v[176:179], v247, s[92:93]
	s_add_u32 s94, s90, 0xc000
	s_addc_u32 s95, s91, 0
	s_nop 0
	global_load_dwordx4 v[180:183], v247, s[94:95]
	s_add_u32 s92, s90, 0x10000
	s_addc_u32 s93, s91, 0
	s_nop 0
	global_load_dwordx4 v[184:187], v247, s[92:93]
	s_add_u32 s94, s90, 0x14000
	s_addc_u32 s95, s91, 0
	s_nop 0
	global_load_dwordx4 v[188:191], v247, s[94:95]
	s_add_u32 s92, s90, 0x18000
	s_addc_u32 s93, s91, 0
	s_nop 0
	global_load_dwordx4 v[192:195], v247, s[92:93]
	s_add_u32 s94, s90, 0x1c000
	s_addc_u32 s95, s91, 0
	s_nop 0
	global_load_dwordx4 v[196:199], v247, s[94:95]
	global_load_dwordx4 v[200:203], v247, s[88:89] offset:128
	s_add_u32 s92, s88, 0x4000
	s_addc_u32 s93, s89, 0
	s_nop 0
	global_load_dwordx4 v[204:207], v247, s[92:93] offset:128
	s_add_u32 s94, s88, 0x8000
	s_addc_u32 s95, s89, 0
	s_nop 0
	global_load_dwordx4 v[212:215], v247, s[94:95] offset:128
	s_add_u32 s92, s88, 0xc000
	s_addc_u32 s93, s89, 0
	s_nop 0
	global_load_dwordx4 v[216:219], v247, s[92:93] offset:128
	s_add_u32 s94, s88, 0x10000
	s_addc_u32 s95, s89, 0
	s_nop 0
	global_load_dwordx4 v[220:223], v247, s[94:95] offset:128
	s_add_u32 s92, s88, 0x14000
	s_addc_u32 s93, s89, 0
	s_nop 0
	global_load_dwordx4 v[224:227], v247, s[92:93] offset:128
	s_add_u32 s94, s88, 0x18000
	s_addc_u32 s95, s89, 0
	s_nop 0
	global_load_dwordx4 v[228:231], v247, s[94:95] offset:128
	s_add_u32 s92, s88, 0x1c000
	s_addc_u32 s93, s89, 0
	s_nop 0
	global_load_dwordx4 v[232:235], v247, s[92:93] offset:128
	s_waitcnt vmcnt(16) lgkmcnt(0)
; DI f32x16 mfma32(bf16x8 a, bf16x8 b, f32x16 c) { return __builtin_amdgcn_mfma_f32_32x32x16_bf16(a, b, c, 0, 0, 0); }
; template <int EPI, int K, int LNI>
; DI void gemm_tail_unit(const Params& p, const bf16_t* __restrict__ A, const bf16_t* __restrict__ Bt, const int un, float* s_aux) {
;     ...
; #pragma unroll 8
;     for (int s = 0; s < KS / 16; ++s) {
;         const bf16x8 a0 = *(const bf16x8*)(ap + s * 16), a1 = *(const bf16x8*)(ap + (size_t)32 * K + s * 16);
;         const bf16x8 b0 = *(const bf16x8*)(bp + s * 16), b1 = *(const bf16x8*)(bp + (size_t)32 * K + s * 16);
;         acc[0][0] = mfma32(a0, b0, acc[0][0]); acc[0][1] = mfma32(a0, b1, acc[0][1]);
;         acc[1][0] = mfma32(a1, b0, acc[1][0]); acc[1][1] = mfma32(a1, b1, acc[1][1]);
;     }
	ds_write_b128 v245, v[84:87]
	ds_write_b128 v245, v[140:143] offset:1152
	ds_write_b128 v245, v[144:147] offset:2304
	ds_write_b128 v245, v[148:151] offset:3456
	ds_write_b128 v245, v[152:155] offset:4608
	ds_write_b128 v245, v[156:159] offset:5760
	ds_write_b128 v245, v[160:163] offset:6912
	ds_write_b128 v245, v[164:167] offset:8064
	s_waitcnt lgkmcnt(0)
	ds_read_b128 v[84:87], v246
	ds_read_b128 v[140:143], v246 offset:32
	ds_read_b128 v[144:147], v246 offset:64
	ds_read_b128 v[148:151], v246 offset:96
	ds_read_b128 v[152:155], v246 offset:4608
	ds_read_b128 v[156:159], v246 offset:4640
	ds_read_b128 v[160:163], v246 offset:4672
	ds_read_b128 v[164:167], v246 offset:4704
	s_waitcnt vmcnt(8) lgkmcnt(0)
	ds_write_b128 v245, v[168:171]
	ds_write_b128 v245, v[172:175] offset:1152
	ds_write_b128 v245, v[176:179] offset:2304
	ds_write_b128 v245, v[180:183] offset:3456
	ds_write_b128 v245, v[184:187] offset:4608
	ds_write_b128 v245, v[188:191] offset:5760
	ds_write_b128 v245, v[192:195] offset:6912
	ds_write_b128 v245, v[196:199] offset:8064
	s_waitcnt lgkmcnt(0)
	ds_read_b128 v[168:171], v246
	ds_read_b128 v[172:175], v246 offset:32
	ds_read_b128 v[176:179], v246 offset:64
	ds_read_b128 v[180:183], v246 offset:96
	ds_read_b128 v[184:187], v246 offset:4608
	ds_read_b128 v[188:191], v246 offset:4640
	ds_read_b128 v[192:195], v246 offset:4672
	ds_read_b128 v[196:199], v246 offset:4704
	s_waitcnt lgkmcnt(0)
	v_mfma_f32_32x32x16_bf16 v[48:63], v[84:87], v[168:171], 0
	v_mfma_f32_32x32x16_bf16 v[32:47], v[84:87], v[184:187], 0
	v_mfma_f32_32x32x16_bf16 v[16:31], v[152:155], v[168:171], 0
	v_mfma_f32_32x32x16_bf16 v[0:15], v[152:155], v[184:187], 0
	v_mfma_f32_32x32x16_bf16 v[48:63], v[140:143], v[172:175], v[48:63]
	v_mfma_f32_32x32x16_bf16 v[32:47], v[140:143], v[188:191], v[32:47]
	v_mfma_f32_32x32x16_bf16 v[16:31], v[156:159], v[172:175], v[16:31]
	v_mfma_f32_32x32x16_bf16 v[0:15], v[156:159], v[188:191], v[0:15]
	v_mfma_f32_32x32x16_bf16 v[48:63], v[144:147], v[176:179], v[48:63]
	v_mfma_f32_32x32x16_bf16 v[32:47], v[144:147], v[192:195], v[32:47]
	v_mfma_f32_32x32x16_bf16 v[16:31], v[160:163], v[176:179], v[16:31]
	v_mfma_f32_32x32x16_bf16 v[0:15], v[160:163], v[192:195], v[0:15]
	v_mfma_f32_32x32x16_bf16 v[48:63], v[148:151], v[180:183], v[48:63]
	v_mfma_f32_32x32x16_bf16 v[32:47], v[148:151], v[196:199], v[32:47]
	v_mfma_f32_32x32x16_bf16 v[16:31], v[164:167], v[180:183], v[16:31]
	v_mfma_f32_32x32x16_bf16 v[0:15], v[164:167], v[196:199], v[0:15]
	global_load_dwordx4 v[84:87], v247, s[90:91] offset:128
	s_add_u32 s94, s90, 0x4000
	s_addc_u32 s95, s91, 0
	s_nop 0
	global_load_dwordx4 v[140:143], v247, s[94:95] offset:128
	s_add_u32 s92, s90, 0x8000
	s_addc_u32 s93, s91, 0
	s_nop 0
	global_load_dwordx4 v[144:147], v247, s[92:93] offset:128
	s_add_u32 s94, s90, 0xc000
	s_addc_u32 s95, s91, 0
	s_nop 0
	global_load_dwordx4 v[148:151], v247, s[94:95] offset:128
	s_add_u32 s92, s90, 0x10000
	s_addc_u32 s93, s91, 0
	s_nop 0
	global_load_dwordx4 v[152:155], v247, s[92:93] offset:128
	s_add_u32 s94, s90, 0x14000
	s_addc_u32 s95, s91, 0
	s_nop 0
	global_load_dwordx4 v[156:159], v247, s[94:95] offset:128
	s_add_u32 s92, s90, 0x18000
	s_addc_u32 s93, s91, 0
	s_nop 0
	global_load_dwordx4 v[160:163], v247, s[92:93] offset:128
	s_add_u32 s94, s90, 0x1c000
	s_addc_u32 s95, s91, 0
	s_nop 0
	global_load_dwordx4 v[164:167], v247, s[94:95] offset:128
	s_waitcnt vmcnt(8) lgkmcnt(0)
	ds_write_b128 v245, v[200:203]
	ds_write_b128 v245, v[204:207] offset:1152
	ds_write_b128 v245, v[212:215] offset:2304
	ds_write_b128 v245, v[216:219] offset:3456
	ds_write_b128 v245, v[220:223] offset:4608
	ds_write_b128 v245, v[224:227] offset:5760
	ds_write_b128 v245, v[228:231] offset:6912
	ds_write_b128 v245, v[232:235] offset:8064
	s_waitcnt lgkmcnt(0)
	ds_read_b128 v[200:203], v246
	ds_read_b128 v[204:207], v246 offset:32
	ds_read_b128 v[212:215], v246 offset:64
	ds_read_b128 v[216:219], v246 offset:96
	ds_read_b128 v[220:223], v246 offset:4608
	ds_read_b128 v[224:227], v246 offset:4640
	ds_read_b128 v[228:231], v246 offset:4672
	ds_read_b128 v[232:235], v246 offset:4704
	s_waitcnt vmcnt(0) lgkmcnt(0)
	ds_write_b128 v245, v[84:87]
	ds_write_b128 v245, v[140:143] offset:1152
	ds_write_b128 v245, v[144:147] offset:2304
	ds_write_b128 v245, v[148:151] offset:3456
	ds_write_b128 v245, v[152:155] offset:4608
	ds_write_b128 v245, v[156:159] offset:5760
	ds_write_b128 v245, v[160:163] offset:6912
	ds_write_b128 v245, v[164:167] offset:8064
	s_waitcnt lgkmcnt(0)
	ds_read_b128 v[84:87], v246
	ds_read_b128 v[140:143], v246 offset:32
	ds_read_b128 v[144:147], v246 offset:64
	ds_read_b128 v[148:151], v246 offset:96
	ds_read_b128 v[152:155], v246 offset:4608
	ds_read_b128 v[156:159], v246 offset:4640
	ds_read_b128 v[160:163], v246 offset:4672
	ds_read_b128 v[164:167], v246 offset:4704
	s_waitcnt lgkmcnt(0)
; DI f32x16 mfma32(bf16x8 a, bf16x8 b, f32x16 c) { return __builtin_amdgcn_mfma_f32_32x32x16_bf16(a, b, c, 0, 0, 0); }
; template <int EPI, int K, int LNI>
; DI void gemm_tail_unit(const Params& p, const bf16_t* __restrict__ A, const bf16_t* __restrict__ Bt, const int un, float* s_aux) {
;     ...
; #pragma unroll 8
;     for (int s = 0; s < KS / 16; ++s) {
;         const bf16x8 a0 = *(const bf16x8*)(ap + s * 16), a1 = *(const bf16x8*)(ap + (size_t)32 * K + s * 16);
;         const bf16x8 b0 = *(const bf16x8*)(bp + s * 16), b1 = *(const bf16x8*)(bp + (size_t)32 * K + s * 16);
;         acc[0][0] = mfma32(a0, b0, acc[0][0]); acc[0][1] = mfma32(a0, b1, acc[0][1]);
;         acc[1][0] = mfma32(a1, b0, acc[1][0]); acc[1][1] = mfma32(a1, b1, acc[1][1]);
;     }
;     float* red = (float*)dsm;
; #pragma unroll
;     for (int i = 0; i < 2; ++i)
; #pragma unroll
;         for (int j = 0; j < 2; ++j)
; #pragma unroll
;             for (int reg = 0; reg < 16; ++reg) red[((w * 4 + i * 2 + j) * 16 + reg) * 64 + lane] = acc[i][j][reg];
	v_mfma_f32_32x32x16_bf16 v[48:63], v[200:203], v[84:87], v[48:63]
	v_mfma_f32_32x32x16_bf16 v[32:47], v[200:203], v[152:155], v[32:47]
	v_mfma_f32_32x32x16_bf16 v[16:31], v[220:223], v[84:87], v[16:31]
	v_mfma_f32_32x32x16_bf16 v[0:15], v[220:223], v[152:155], v[0:15]
	v_mfma_f32_32x32x16_bf16 v[48:63], v[204:207], v[140:143], v[48:63]
	v_mfma_f32_32x32x16_bf16 v[32:47], v[204:207], v[156:159], v[32:47]
	v_mfma_f32_32x32x16_bf16 v[16:31], v[224:227], v[140:143], v[16:31]
	v_mfma_f32_32x32x16_bf16 v[0:15], v[224:227], v[156:159], v[0:15]
	v_mfma_f32_32x32x16_bf16 v[48:63], v[212:215], v[144:147], v[48:63]
	v_mfma_f32_32x32x16_bf16 v[32:47], v[212:215], v[160:163], v[32:47]
	v_mfma_f32_32x32x16_bf16 v[16:31], v[228:231], v[144:147], v[16:31]
	v_mfma_f32_32x32x16_bf16 v[0:15], v[228:231], v[160:163], v[0:15]
	v_mfma_f32_32x32x16_bf16 v[48:63], v[216:219], v[148:151], v[48:63]
	v_mfma_f32_32x32x16_bf16 v[32:47], v[216:219], v[164:167], v[32:47]
	v_mfma_f32_32x32x16_bf16 v[16:31], v[232:235], v[148:151], v[16:31]
	v_mfma_f32_32x32x16_bf16 v[0:15], v[232:235], v[164:167], v[0:15]
	s_nop 7
	s_nop 3
	s_cmp_lt_i32 s20, 64
	ds_write2st64_b32 v117, v48, v49 offset1:1
	ds_write2st64_b32 v117, v50, v51 offset0:2 offset1:3
	ds_write2st64_b32 v117, v52, v53 offset0:4 offset1:5
	ds_write2st64_b32 v117, v54, v55 offset0:6 offset1:7
	ds_write2st64_b32 v117, v56, v57 offset0:8 offset1:9
	ds_write2st64_b32 v117, v58, v59 offset0:10 offset1:11
	ds_write2st64_b32 v117, v60, v61 offset0:12 offset1:13
	ds_write2st64_b32 v117, v62, v63 offset0:14 offset1:15
	ds_write2st64_b32 v117, v32, v33 offset0:16 offset1:17
	ds_write2st64_b32 v117, v34, v35 offset0:18 offset1:19
	ds_write2st64_b32 v117, v36, v37 offset0:20 offset1:21
	ds_write2st64_b32 v117, v38, v39 offset0:22 offset1:23
	ds_write2st64_b32 v117, v40, v41 offset0:24 offset1:25
	ds_write2st64_b32 v117, v42, v43 offset0:26 offset1:27
	ds_write2st64_b32 v117, v44, v45 offset0:28 offset1:29
	ds_write2st64_b32 v117, v46, v47 offset0:30 offset1:31
	ds_write2st64_b32 v117, v16, v17 offset0:32 offset1:33
	ds_write2st64_b32 v117, v18, v19 offset0:34 offset1:35
	ds_write2st64_b32 v117, v20, v21 offset0:36 offset1:37
	ds_write2st64_b32 v117, v22, v23 offset0:38 offset1:39
	ds_write2st64_b32 v117, v24, v25 offset0:40 offset1:41
	ds_write2st64_b32 v117, v26, v27 offset0:42 offset1:43
	ds_write2st64_b32 v117, v28, v29 offset0:44 offset1:45
	ds_write2st64_b32 v117, v30, v31 offset0:46 offset1:47
	ds_write2st64_b32 v117, v0, v1 offset0:48 offset1:49
	ds_write2st64_b32 v117, v2, v3 offset0:50 offset1:51
	ds_write2st64_b32 v117, v4, v5 offset0:52 offset1:53
	ds_write2st64_b32 v117, v6, v7 offset0:54 offset1:55
	ds_write2st64_b32 v117, v8, v9 offset0:56 offset1:57
	ds_write2st64_b32 v117, v10, v11 offset0:58 offset1:59
	ds_write2st64_b32 v117, v12, v13 offset0:60 offset1:61
	ds_write2st64_b32 v117, v14, v15 offset0:62 offset1:63
	s_waitcnt lgkmcnt(0)
	s_barrier
; DI bf16_t f2bf(float x) { return (bf16_t)(cvt_pk(x, 0.f) & 0xffffu); }
;     ...
;     } else if (EPI == EPI_FFN1) {
;         bf16_t* d = (bf16_t*)(p.ws + OFF_U) + (size_t)row0 * 4096 + col;
; #pragma unroll
;         for (int e = 0; e < 4; ++e) { const float t = fmaxf(v[e], 0.f); d[(size_t)e * 4096] = f2bf(t * t); }
; template <int EPI, int K, int LNI>
; DI void gemm_tail_unit(const Params& p, const bf16_t* __restrict__ A, const bf16_t* __restrict__ Bt, const int un, float* s_aux) {
;     ...
;     {
;         const int tile = w >> 1, i = tile >> 1, j = tile & 1;
; #pragma unroll
;         for (int gg = 0; gg < 2; ++gg) {
;             const int g = 2 * (w & 1) + gg;
;             float v[4];
; #pragma unroll
;             for (int e = 0; e < 4; ++e) {
;                 float sacc = 0.f;
; #pragma unroll
;                 for (int wv = 0; wv < 8; ++wv) sacc += red[((wv * 4 + tile) * 16 + 4 * g + e) * 64 + lane];
;                 v[e] = sacc;
;             }
;             const int lrow0 = i * 32 + 8 * g + 4 * h;
	ds_read_b32 v32, v122
	ds_read_b32 v33, v123
	ds_read_b32 v34, v124
	ds_read_b32 v35, v125
	ds_read_b32 v36, v128
	ds_read_b32 v37, v96
	ds_read_b32 v38, v97
	ds_read_b32 v39, v129
	ds_read2st64_b32 v[0:1], v121 offset1:1
	ds_read2st64_b32 v[2:3], v121 offset0:64 offset1:65
	ds_read2st64_b32 v[4:5], v121 offset0:66 offset1:67
	ds_read2st64_b32 v[6:7], v121 offset0:2 offset1:3
	ds_read2st64_b32 v[8:9], v121 offset0:128 offset1:129
	ds_read2st64_b32 v[10:11], v121 offset0:192 offset1:193
	ds_read2st64_b32 v[12:13], v121 offset0:194 offset1:195
	ds_read2st64_b32 v[14:15], v121 offset0:130 offset1:131
	ds_read_b32 v40, v130
	ds_read_b32 v41, v131
	ds_read_b32 v42, v132
	ds_read_b32 v43, v133
	ds_read_b32 v44, v98
	ds_read_b32 v45, v99
	ds_read_b32 v46, v100
	ds_read_b32 v47, v101
	ds_read_b32 v48, v126
	ds_read_b32 v49, v134
	ds_read_b32 v50, v135
	ds_read_b32 v51, v136
	ds_read_b32 v52, v102
	ds_read_b32 v53, v103
	ds_read_b32 v54, v104
	ds_read_b32 v55, v105
	ds_read2st64_b32 v[16:17], v88 offset1:1
	ds_read2st64_b32 v[18:19], v88 offset0:64 offset1:65
	ds_read2st64_b32 v[20:21], v88 offset0:66 offset1:67
	ds_read2st64_b32 v[22:23], v88 offset0:2 offset1:3
	ds_read2st64_b32 v[24:25], v88 offset0:128 offset1:129
	ds_read2st64_b32 v[26:27], v88 offset0:192 offset1:193
	ds_read2st64_b32 v[28:29], v88 offset0:194 offset1:195
	ds_read2st64_b32 v[30:31], v88 offset0:130 offset1:131
	ds_read_b32 v56, v110
	ds_read_b32 v57, v106
	ds_read_b32 v58, v107
	ds_read_b32 v59, v108
	ds_read_b32 v60, v109
	ds_read_b32 v61, v111
	ds_read_b32 v62, v116
	ds_read_b32 v63, v118
	s_waitcnt lgkmcnt(14)
	v_add_f32_e32 v0, 0, v0
	v_add_f32_e32 v1, 0, v1
	v_add_f32_e32 v6, 0, v6
	v_add_f32_e32 v7, 0, v7
	v_add_f32_e32 v16, 0, v16
	v_add_f32_e32 v17, 0, v17
	s_waitcnt lgkmcnt(12)
	v_add_f32_e32 v22, 0, v22
	v_add_f32_e32 v23, 0, v23
	v_add_f32_e32 v0, v0, v2
	v_add_f32_e32 v1, v1, v3
	v_add_f32_e32 v2, v6, v4
	v_add_f32_e32 v3, v7, v5
	v_add_f32_e32 v4, v16, v18
	v_add_f32_e32 v5, v17, v19
	v_add_f32_e32 v6, v22, v20
	v_add_f32_e32 v7, v23, v21
	v_add_f32_e32 v0, v0, v8
	v_add_f32_e32 v1, v1, v9
	v_add_f32_e32 v2, v2, v14
	v_add_f32_e32 v3, v3, v15
	s_waitcnt lgkmcnt(11)
	v_add_f32_e32 v4, v4, v24
	v_add_f32_e32 v5, v5, v25
	s_waitcnt lgkmcnt(8)
	v_add_f32_e32 v6, v6, v30
	v_add_f32_e32 v7, v7, v31
	v_add_f32_e32 v0, v0, v10
	v_add_f32_e32 v1, v1, v11
	v_add_f32_e32 v2, v2, v12
	v_add_f32_e32 v3, v3, v13
	v_add_f32_e32 v4, v4, v26
	v_add_f32_e32 v5, v5, v27
	v_add_f32_e32 v6, v6, v28
	v_add_f32_e32 v7, v7, v29
	v_add_f32_e32 v0, v0, v32
	v_add_f32_e32 v1, v1, v36
	v_add_f32_e32 v2, v2, v40
	v_add_f32_e32 v3, v3, v44
	v_add_f32_e32 v4, v4, v48
	v_add_f32_e32 v5, v5, v52
	s_waitcnt lgkmcnt(7)
	v_add_f32_e32 v6, v6, v56
	s_waitcnt lgkmcnt(3)
	v_add_f32_e32 v7, v7, v60
	v_add_f32_e32 v0, v0, v33
	v_add_f32_e32 v1, v1, v37
	v_add_f32_e32 v2, v2, v41
	v_add_f32_e32 v3, v3, v45
	v_add_f32_e32 v4, v4, v49
	v_add_f32_e32 v5, v5, v53
	v_add_f32_e32 v6, v6, v57
	s_waitcnt lgkmcnt(2)
	v_add_f32_e32 v7, v7, v61
	v_add_f32_e32 v0, v0, v34
	v_add_f32_e32 v1, v1, v38
	v_add_f32_e32 v2, v2, v42
	v_add_f32_e32 v3, v3, v46
	v_add_f32_e32 v4, v4, v50
	v_add_f32_e32 v5, v5, v54
	v_add_f32_e32 v6, v6, v58
	s_waitcnt lgkmcnt(1)
	v_add_f32_e32 v7, v7, v62
	v_add_f32_e32 v0, v0, v35
	v_add_f32_e32 v1, v1, v39
	v_add_f32_e32 v2, v2, v43
	v_add_f32_e32 v3, v3, v47
	v_add_f32_e32 v4, v4, v51
	v_add_f32_e32 v5, v5, v55
	v_add_f32_e32 v6, v6, v59
	s_waitcnt lgkmcnt(0)
	v_add_f32_e32 v7, v7, v63
	v_max_f32_e32 v0, 0, v0
	v_max_f32_e32 v1, 0, v1
	v_max_f32_e32 v2, 0, v2
	v_max_f32_e32 v3, 0, v3
	v_max_f32_e32 v4, 0, v4
	v_max_f32_e32 v5, 0, v5
	v_max_f32_e32 v6, 0, v6
	v_max_f32_e32 v7, 0, v7
	v_mul_f32_e32 v0, v0, v0
	v_mul_f32_e32 v1, v1, v1
	v_mul_f32_e32 v2, v2, v2
	v_mul_f32_e32 v3, v3, v3
	v_mul_f32_e32 v4, v4, v4
	v_mul_f32_e32 v5, v5, v5
	v_mul_f32_e32 v6, v6, v6
	v_mul_f32_e32 v7, v7, v7
	v_cvt_pk_bf16_f32 v0, v0, s0
	v_cvt_pk_bf16_f32 v1, v1, s0
	v_cvt_pk_bf16_f32 v2, v2, s0
	v_cvt_pk_bf16_f32 v3, v3, s0
	v_cvt_pk_bf16_f32 v4, v4, s0
	v_cvt_pk_bf16_f32 v5, v5, s0
	v_cvt_pk_bf16_f32 v6, v6, s0
	v_cvt_pk_bf16_f32 v7, v7, s0
	global_store_short v[74:75], v0, off
	global_store_short v[76:77], v1, off
	global_store_short v[78:79], v2, off
	global_store_short v[80:81], v3, off
	global_store_short v[72:73], v4, off
	global_store_short v[68:69], v5, off
	global_store_short v[70:71], v6, off
	global_store_short v[64:65], v7, off
	s_barrier
	s_cbranch_scc1 .LBB0_1861
